# qkv phase rewritten by hand on the pipelined GEMM core: mixed Q/KV tile stream, cooperative row-rms scale via LDS, in-lane rope32, LDS-transposed V store
# speedup vs baseline: 1.1258x; 1.0182x over previous
; DI int opqv(int x) { asm volatile("" : "+v"(x)); return x; }
; DI char* opq(char* p) { asm volatile("" : "+s"(p)); return p; }
; DI void qkv_phase(const Params& p, int j, char* smem) {
;   const int tid = opqv(threadIdx.x), lane = tid & 63, w = tid >> 6, wm = w >> 2, wn = w & 3, l32 = lane & 31, hf = lane >> 5;
;   char* ws = opq(p.ws);
;   const u16* zc = (const u16*)(ws + OFF_ZC);
;   const u16* Wq = (const u16*)(ws + OFF_W_UQ) + (size_t)j * 768 * 384;
;   const u16* Wkv = (const u16*)(ws + OFF_W_UKV) + (size_t)j * 1024 * 256;
;   u16* Qb = (u16*)(ws + OFF_QB); u16* Kb = (u16*)(ws + OFF_KB); u16* Vt = (u16*)(ws + OFF_VT);
;   const float2* rt32 = (const float2*)(ws + OFF_RT32);
;   float* rsc = (float*)(smem + SMEM_GEMM);
;   for (int lt0 = blockIdx.x >> 3; lt0 < 16 * 7; lt0 += gridDim.x >> 3) {
;     const bool isq = lt0 < 16 * 3;
;     int mt, nt;
;     if (isq) tile_map(lt0, 16, 3, 16, 1, mt, nt); else tile_map(lt0 - 16 * 3, 16, 4, 8, 4, mt, nt);
;     const int m0 = mt * 256, n0 = nt * 256;
;     const int coff = isq ? 0 : 384, ncols = isq ? 384 : 256;
;     {
;       const int row = tid >> 1, half = tid & 1, nh = ncols / 2;
.LBB0_158:
	s_andn2_b64 vcc, exec, s[0:1]
	s_mov_b64 s[0:1], -1
	s_cbranch_vccnz .LBB0_710
	v_readlane_b32 s0, v254, 24
	s_mov_b64 s[6:7], -1
	s_mov_b64 s[4:5], 0
	s_cmp_lt_i32 s0, 1
	s_mov_b64 s[0:1], 0
	s_cbranch_scc1 .LBB0_593
	v_readlane_b32 s0, v254, 24
	s_cmp_eq_u32 s0, 1
	s_mov_b64 s[0:1], -1
	s_cbranch_scc0 .LBB0_600
	v_readlane_b32 s6, v251, 51
	v_readlane_b32 s0, v251, 13
	v_readlane_b32 s7, v251, 52
	v_mov_b32_e32 v0, v182
	v_readlane_b32 s1, v251, 14
	s_andn2_b64 vcc, exec, s[6:7]
	s_cbranch_vccnz .LBB0_599
	v_readlane_b32 s28, v253, 48
	v_readlane_b32 s30, v253, 50
	s_cmp_ge_u32 s28, 0x70
	s_cbranch_scc1 .LBB0_599
	v_readlane_b32 s12, v254, 25
	v_readlane_b32 s31, v251, 0
	s_mul_i32 s6, s12, 0x90000
	s_add_u32 s6, s0, s6
	s_addc_u32 s7, s1, 0
	s_add_u32 s6, s6, 0x1724100
	s_addc_u32 s7, s7, 0
	s_lshl_b32 s8, s12, 19
	s_add_u32 s8, s0, s8
	s_addc_u32 s9, s1, 0
	s_add_u32 s8, s8, 0x1844100
	s_addc_u32 s9, s9, 0
	s_add_u32 s10, s0, 0xd004100
	s_addc_u32 s11, s1, 0
	s_and_b32 s31, s31, 7
	s_lshl_b32 s31, s31, 4
	v_lshrrev_b32_e32 v228, 6, v182
	v_and_b32_e32 v229, 63, v182
	v_readfirstlane_b32 s15, v228
	v_and_b32_e32 v230, 31, v229
	v_lshrrev_b32_e32 v231, 5, v229
	v_lshrrev_b32_e32 v232, 3, v229
	v_and_b32_e32 v233, 7, v229
	s_lshl_b32 s14, s15, 12
	s_add_u32 s14, s14, 32
	v_lshrrev_b32_e32 v234, 1, v232
	v_xor_b32_e32 v234, v233, v234
	v_lshlrev_b32_e32 v234, 4, v234
	s_lshl_b32 s34, s15, 2
	s_add_u32 s34, s34, 0
	s_lshl_b32 s34, s34, 3
	v_add_u32_e32 v235, s34, v232
	s_movk_i32 s35, 0x500
	v_mad_u32_u24 v220, v235, s35, v234
	v_lshrrev_b32_e32 v234, 1, v232
	v_add_u32_e32 v234, 4, v234
	v_xor_b32_e32 v234, v233, v234
	v_lshlrev_b32_e32 v234, 4, v234
	s_lshl_b32 s34, s15, 2
	s_add_u32 s34, s34, 1
	s_lshl_b32 s34, s34, 3
	v_add_u32_e32 v235, s34, v232
	s_movk_i32 s35, 0x500
	v_mad_u32_u24 v221, v235, s35, v234
	v_lshrrev_b32_e32 v234, 1, v232
	v_xor_b32_e32 v234, v233, v234
	v_lshlrev_b32_e32 v234, 4, v234
	s_lshl_b32 s34, s15, 2
	s_add_u32 s34, s34, 2
	s_lshl_b32 s34, s34, 3
	v_add_u32_e32 v235, s34, v232
	s_movk_i32 s35, 0x500
	v_mad_u32_u24 v222, v235, s35, v234
	v_lshrrev_b32_e32 v234, 1, v232
	v_add_u32_e32 v234, 4, v234
	v_xor_b32_e32 v234, v233, v234
	v_lshlrev_b32_e32 v234, 4, v234
	s_lshl_b32 s34, s15, 2
	s_add_u32 s34, s34, 3
	s_lshl_b32 s34, s34, 3
	v_add_u32_e32 v235, s34, v232
	s_movk_i32 s35, 0x500
	v_mad_u32_u24 v223, v235, s35, v234
	v_lshrrev_b32_e32 v236, 1, v230
	v_and_b32_e32 v236, 7, v236
	s_lshr_b32 s34, s15, 2
	s_and_b32 s35, s15, 3
	s_lshl_b32 s36, s34, 14
	s_add_u32 s36, s36, 32
	s_lshl_b32 s37, s35, 13
	s_add_u32 s37, s37, 0x8020
	v_lshlrev_b32_e32 v237, 7, v230
	v_add_u32_e32 v238, s37, v237
	v_add_u32_e32 v237, s36, v237
	v_add_u32_e32 v239, 0, v231
	v_xor_b32_e32 v239, v239, v236
	v_lshlrev_b32_e32 v239, 4, v239
	v_add_u32_e32 v204, v237, v239
	v_add_u32_e32 v212, v238, v239
	v_add_u32_e32 v208, 0x10000, v204
	v_add_u32_e32 v216, 0x10000, v212
	v_add_u32_e32 v239, 2, v231
	v_xor_b32_e32 v239, v239, v236
	v_lshlrev_b32_e32 v239, 4, v239
	v_add_u32_e32 v205, v237, v239
	v_add_u32_e32 v213, v238, v239
	v_add_u32_e32 v209, 0x10000, v205
	v_add_u32_e32 v217, 0x10000, v213
	v_add_u32_e32 v239, 4, v231
	v_xor_b32_e32 v239, v239, v236
	v_lshlrev_b32_e32 v239, 4, v239
	v_add_u32_e32 v206, v237, v239
	v_add_u32_e32 v214, v238, v239
	v_add_u32_e32 v210, 0x10000, v206
	v_add_u32_e32 v218, 0x10000, v214
	v_add_u32_e32 v239, 6, v231
	v_xor_b32_e32 v239, v239, v236
	v_lshlrev_b32_e32 v239, 4, v239
	v_add_u32_e32 v207, v237, v239
	v_add_u32_e32 v215, v238, v239
	v_add_u32_e32 v211, 0x10000, v207
	v_add_u32_e32 v219, 0x10000, v215
	s_add_u32 s36, s14, 0x18000
	v_lshlrev_b32_e32 v234, 7, v230
	v_lshlrev_b32_e32 v235, 3, v231
	v_add3_u32 v234, v234, v235, s36
	v_and_b32_e32 v235, 7, v230
	v_mov_b32_e32 v178, v235
	v_xor_b32_e32 v179, 1, v235
	v_xor_b32_e32 v180, 2, v235
	v_xor_b32_e32 v181, 3, v235
	v_xor_b32_e32 v188, 4, v235
	v_xor_b32_e32 v189, 5, v235
	v_xor_b32_e32 v190, 6, v235
	v_xor_b32_e32 v191, 7, v235
	v_lshl_add_u32 v178, v178, 4, v234
	v_lshl_add_u32 v179, v179, 4, v234
	v_lshl_add_u32 v180, v180, 4, v234
	v_lshl_add_u32 v181, v181, 4, v234
	v_lshl_add_u32 v188, v188, 4, v234
	v_lshl_add_u32 v189, v189, 4, v234
	v_lshl_add_u32 v190, v190, 4, v234
	v_lshl_add_u32 v191, v191, 4, v234
	v_xor_b32_e32 v194, v232, v233
	v_lshlrev_b32_e32 v194, 4, v194
	v_lshl_add_u32 v194, v232, 7, v194
	v_add_u32_e32 v194, s36, v194
	s_lshl_b32 s12, s34, 7
	s_mov_b32 s13, s35
	s_lshl_b32 s34, s15, 2
	s_add_u32 s34, s34, 0
	s_lshl_b32 s34, s34, 3
	v_add_u32_e32 v224, s34, v232
	s_lshl_b32 s34, s15, 2
	s_add_u32 s34, s34, 1
	s_lshl_b32 s34, s34, 3
	v_add_u32_e32 v225, s34, v232
	s_lshl_b32 s34, s15, 2
	s_add_u32 s34, s34, 2
	s_lshl_b32 s34, s34, 3
	v_add_u32_e32 v226, s34, v232
	s_lshl_b32 s34, s15, 2
	s_add_u32 s34, s34, 3
	s_lshl_b32 s34, s34, 3
	v_add_u32_e32 v227, s34, v232
	v_lshrrev_b32_e32 v228, 1, v232
	v_xor_b32_e32 v228, v233, v228
	v_lshlrev_b32_e32 v228, 4, v228
	v_lshrrev_b32_e32 v229, 1, v232
	v_add_u32_e32 v229, 4, v229
	v_xor_b32_e32 v229, v233, v229
	v_lshlrev_b32_e32 v229, 4, v229
	v_and_b32_e32 v247, 63, v182
	v_lshrrev_b32_e32 v246, 3, v247
	v_and_b32_e32 v245, 7, v247
	v_and_b32_e32 v244, 31, v247
	v_lshrrev_b32_e32 v243, 5, v247
	v_lshlrev_b32_e32 v195, 4, v245
	s_movk_i32 s34, 0x600
	v_mad_u32_u24 v195, v246, s34, v195
	v_lshlrev_b32_e32 v197, 4, v245
	s_movk_i32 s34, 0x680
	v_mad_u32_u24 v197, v246, s34, v197
	v_lshrrev_b32_e32 v242, 2, v245
	v_lshl_add_u32 v196, v242, 7, v195
	v_lshrrev_b32_e32 v242, 2, v247
	v_and_b32_e32 v241, 3, v247
	v_lshlrev_b32_e32 v234, 4, v241
	s_mov_b32 s34, 0x8080
	v_mad_u32_u24 v234, v242, s34, v234
	s_add_u32 s34, s14, 0x18000
	v_lshlrev_b32_e32 v235, 8, v243
	v_lshl_add_u32 v235, v244, 1, v235
	v_add_u32_e32 v235, s34, v235
	v_lshlrev_b32_e32 v236, 4, v241
	v_lshl_add_u32 v236, v242, 6, v236
	v_add_u32_e32 v236, s34, v236
	s_lshl_b32 s34, s12, 2
	s_add_u32 s34, s34, 0x20020
	v_lshl_add_u32 v237, v244, 2, s34
	v_lshrrev_b32_e32 v242, 1, v182
	s_movk_i32 s34, 0x500
	v_mul_u32_u24_e32 v238, s34, v242
	v_lshlrev_b32_e32 v239, 2, v242
	v_add_u32_e32 v239, 0x20020, v239
	v_lshlrev_b32_e32 v160, 7, v244
	v_lshl_add_u32 v160, v243, 5, v160
	s_mov_b32 s27, s28
	s_mov_b32 s26, 0
	s_cmp_lt_u32 s27, 48
	s_cbranch_scc0 .Lqk_dec_kv1
	s_and_b32 s53, s27, 15
	s_add_u32 s53, s53, s31
	s_lshr_b32 s54, s27, 4
	s_mov_b32 s52, 1
	s_branch .Lqk_dec_done1
; DI void qkv_phase(const Params& p, int j, char* smem) {
;     ...
;   for (int lt0 = blockIdx.x >> 3; lt0 < 16 * 7; lt0 += gridDim.x >> 3) {
;     const bool isq = lt0 < 16 * 3;
;     int mt, nt;
;     if (isq) tile_map(lt0, 16, 3, 16, 1, mt, nt); else tile_map(lt0 - 16 * 3, 16, 4, 8, 4, mt, nt);
;     const int m0 = mt * 256, n0 = nt * 256;
;     const int coff = isq ? 0 : 384, ncols = isq ? 384 : 256;
.Lqk_dec_kv1:
	s_sub_u32 s54, s27, 48
	s_lshr_b32 s53, s54, 5
	s_lshl_b32 s53, s53, 3
	s_bfe_u32 s52, s54, 0x30002
	s_add_u32 s53, s53, s52
	s_add_u32 s53, s53, s31
	s_and_b32 s54, s54, 3
	s_mov_b32 s52, 0
.Lqk_dec_done1:
	s_mul_i32 s55, s53, 0x50000
	s_add_u32 s22, s10, s55
	s_addc_u32 s23, s11, 0
	s_cmp_eq_u32 s52, 1
	s_cbranch_scc0 .Lqk_cb_kv2
	s_mul_i32 s55, s54, 0x30000
	s_add_u32 s24, s6, s55
	s_addc_u32 s25, s7, 0
	s_mov_b32 s20, 6
	s_movk_i32 s29, 0x300
	s_branch .Lqk_cb_done2
.Lqk_cb_kv2:
	s_add_u32 s22, s22, 0x300
	s_addc_u32 s23, s23, 0
	s_mul_i32 s55, s54, 0x20000
	s_add_u32 s24, s8, s55
	s_addc_u32 s25, s9, 0
	s_mov_b32 s20, 4
	s_movk_i32 s29, 0x200
.Lqk_cb_done2:
	v_mad_u32_u24 v230, v224, s29, v228
	v_mad_u32_u24 v231, v225, s29, v229
	v_mad_u32_u24 v232, v226, s29, v228
	v_mad_u32_u24 v233, v227, s29, v229
	s_add_u32 m0, s14, 0x0
	s_nop 0
	global_load_lds_dwordx4 v220, s[22:23]
	s_add_u32 m0, s14, 0x8000
	s_nop 0
	global_load_lds_dwordx4 v230, s[24:25]
	s_add_u32 m0, s14, 0x400
	s_nop 0
	global_load_lds_dwordx4 v221, s[22:23]
	s_add_u32 m0, s14, 0x8400
	s_nop 0
	global_load_lds_dwordx4 v231, s[24:25]
	s_add_u32 m0, s14, 0x800
	s_nop 0
	global_load_lds_dwordx4 v222, s[22:23]
	s_add_u32 m0, s14, 0x8800
	s_nop 0
	global_load_lds_dwordx4 v232, s[24:25]
	s_add_u32 m0, s14, 0xc00
	s_nop 0
	global_load_lds_dwordx4 v223, s[22:23]
	s_add_u32 m0, s14, 0x8c00
	s_nop 0
	global_load_lds_dwordx4 v233, s[24:25]
	s_add_u32 s22, s22, 0x80
	s_addc_u32 s23, s23, 0
	s_add_u32 s24, s24, 0x80
	s_addc_u32 s25, s25, 0
	s_add_u32 s26, s26, 1
	s_cmp_eq_u32 s26, s20
	s_cbranch_scc0 .Lqk1_cadv_done
	s_mov_b32 s26, 0
	s_add_u32 s27, s27, s30
	s_cmp_lt_u32 s27, 0x70
	s_cbranch_scc1 .Lqk1_cadv_new
	s_lshl_b32 s34, s20, 7
	s_sub_u32 s22, s22, s34
	s_subb_u32 s23, s23, 0
	s_sub_u32 s24, s24, s34
	s_subb_u32 s25, s25, 0
	s_branch .Lqk1_cadv_done
.Lqk1_cadv_new:
	s_cmp_lt_u32 s27, 48
	s_cbranch_scc0 .Lqk_dec_kv3
	s_and_b32 s53, s27, 15
	s_add_u32 s53, s53, s31
	s_lshr_b32 s54, s27, 4
	s_mov_b32 s52, 1
	s_branch .Lqk_dec_done3

.Lqk_cb_done4:
	v_mad_u32_u24 v230, v224, s29, v228
	v_mad_u32_u24 v231, v225, s29, v229
	v_mad_u32_u24 v232, v226, s29, v228
	v_mad_u32_u24 v233, v227, s29, v229
.Lqk1_cadv_done:
	s_add_u32 m0, s14, 0x10000
	s_nop 0
	global_load_lds_dwordx4 v220, s[22:23]
	s_add_u32 m0, s14, 0x18000
	s_nop 0
	global_load_lds_dwordx4 v230, s[24:25]
	s_add_u32 m0, s14, 0x10400
	s_nop 0
	global_load_lds_dwordx4 v221, s[22:23]
	s_add_u32 m0, s14, 0x18400
	s_nop 0
	global_load_lds_dwordx4 v231, s[24:25]
	s_add_u32 m0, s14, 0x10800
	s_nop 0
	global_load_lds_dwordx4 v222, s[22:23]
	s_add_u32 m0, s14, 0x18800
	s_nop 0
	global_load_lds_dwordx4 v232, s[24:25]
	s_add_u32 m0, s14, 0x10c00
	s_nop 0
	global_load_lds_dwordx4 v223, s[22:23]
	s_add_u32 m0, s14, 0x18c00
	s_nop 0
	global_load_lds_dwordx4 v233, s[24:25]
	s_add_u32 s22, s22, 0x80
	s_addc_u32 s23, s23, 0
	s_add_u32 s24, s24, 0x80
	s_addc_u32 s25, s25, 0
	s_add_u32 s26, s26, 1
	s_cmp_eq_u32 s26, s20
	s_cbranch_scc0 .Lqk2_cadv_done
	s_mov_b32 s26, 0
	s_add_u32 s27, s27, s30
	s_cmp_lt_u32 s27, 0x70
	s_cbranch_scc1 .Lqk2_cadv_new
	s_lshl_b32 s34, s20, 7
	s_sub_u32 s22, s22, s34
	s_subb_u32 s23, s23, 0
	s_sub_u32 s24, s24, s34
	s_subb_u32 s25, s25, 0
	s_branch .Lqk2_cadv_done

; #define RAWBAR() { asm volatile("s_waitcnt vmcnt(0) lgkmcnt(0)" ::: "memory"); __builtin_amdgcn_s_barrier(); }
;     ...
;   if (V != 1) GLDS(0, 0);
;   RAWBAR();
;   for (int kt = 0; kt < nk; kt += 2) {
;     if (V != 1) GLDS(kt + 1, 1);
;     if (V != 2) COMPUTE(0);
;     RAWBAR();
;     if (V != 1) if (kt + 2 < nk) GLDS(kt + 2, 0);
;     if (V != 2) COMPUTE(1);
;     RAWBAR();
;   }
; DI void qkv_phase(const Params& p, int j, char* smem) {
;     ...
;   for (int lt0 = blockIdx.x >> 3; lt0 < 16 * 7; lt0 += gridDim.x >> 3) {
;     const bool isq = lt0 < 16 * 3;
;     int mt, nt;
;     if (isq) tile_map(lt0, 16, 3, 16, 1, mt, nt); else tile_map(lt0 - 16 * 3, 16, 4, 8, 4, mt, nt);
;     const int m0 = mt * 256, n0 = nt * 256;
;     const int coff = isq ? 0 : 384, ncols = isq ? 384 : 256;
.Lqk_tile:
	s_cmp_lt_u32 s28, 48
	s_cbranch_scc0 .Lqk_dec_kv7
	s_and_b32 s61, s28, 15
	s_add_u32 s61, s61, s31
	s_lshr_b32 s62, s28, 4
	s_mov_b32 s60, 1
	s_branch .Lqk_dec_done7
.Lqk_dec_kv7:
	s_sub_u32 s62, s28, 48
	s_lshr_b32 s61, s62, 5
	s_lshl_b32 s61, s61, 3
	s_bfe_u32 s60, s62, 0x30002
	s_add_u32 s61, s61, s60
	s_add_u32 s61, s61, s31
	s_and_b32 s62, s62, 3
	s_mov_b32 s60, 0
.Lqk_dec_done7:
	s_mov_b32 s63, s60
	s_waitcnt lgkmcnt(6)
	v_mfma_f32_32x32x16_bf16 v[0:15], v[162:165], v[128:131], 0
	v_mfma_f32_32x32x16_bf16 v[16:31], v[166:169], v[128:131], 0
	ds_read_b128 v[128:131], v206
	v_mfma_f32_32x32x16_bf16 v[32:47], v[162:165], v[132:135], 0
	v_mfma_f32_32x32x16_bf16 v[48:63], v[166:169], v[132:135], 0
	ds_read_b128 v[132:135], v206 offset:4096
	v_mfma_f32_32x32x16_bf16 v[64:79], v[162:165], v[136:139], 0
	v_mfma_f32_32x32x16_bf16 v[80:95], v[166:169], v[136:139], 0
	ds_read_b128 v[136:139], v206 offset:8192
	v_mfma_f32_32x32x16_bf16 v[96:111], v[162:165], v[140:143], 0
	v_mfma_f32_32x32x16_bf16 v[112:127], v[166:169], v[140:143], 0
	ds_read_b128 v[140:143], v206 offset:12288
	ds_read_b128 v[162:165], v214
	ds_read_b128 v[166:169], v214 offset:4096
	s_waitcnt lgkmcnt(6)
	v_mfma_f32_32x32x16_bf16 v[0:15], v[170:173], v[144:147], v[0:15]
	v_mfma_f32_32x32x16_bf16 v[16:31], v[174:177], v[144:147], v[16:31]
	ds_read_b128 v[144:147], v207
	v_mfma_f32_32x32x16_bf16 v[32:47], v[170:173], v[148:151], v[32:47]
	v_mfma_f32_32x32x16_bf16 v[48:63], v[174:177], v[148:151], v[48:63]
	ds_read_b128 v[148:151], v207 offset:4096
	v_mfma_f32_32x32x16_bf16 v[64:79], v[170:173], v[152:155], v[64:79]
	v_mfma_f32_32x32x16_bf16 v[80:95], v[174:177], v[152:155], v[80:95]
	ds_read_b128 v[152:155], v207 offset:8192
	v_mfma_f32_32x32x16_bf16 v[96:111], v[170:173], v[156:159], v[96:111]
	v_mfma_f32_32x32x16_bf16 v[112:127], v[174:177], v[156:159], v[112:127]
	ds_read_b128 v[156:159], v207 offset:12288
	ds_read_b128 v[170:173], v215
	ds_read_b128 v[174:177], v215 offset:4096
	s_waitcnt vmcnt(0) lgkmcnt(0)
	s_barrier
	s_add_u32 m0, s14, 0x0
	v_mfma_f32_32x32x16_bf16 v[0:15], v[162:165], v[128:131], v[0:15]
	global_load_lds_dwordx4 v220, s[22:23]
	s_add_u32 m0, s14, 0x8000
	v_mfma_f32_32x32x16_bf16 v[16:31], v[166:169], v[128:131], v[16:31]
	global_load_lds_dwordx4 v230, s[24:25]
	ds_read_b128 v[128:131], v208
	s_add_u32 m0, s14, 0x400
	v_mfma_f32_32x32x16_bf16 v[32:47], v[162:165], v[132:135], v[32:47]
	global_load_lds_dwordx4 v221, s[22:23]
	s_add_u32 m0, s14, 0x8400
	v_mfma_f32_32x32x16_bf16 v[48:63], v[166:169], v[132:135], v[48:63]
	global_load_lds_dwordx4 v231, s[24:25]
	ds_read_b128 v[132:135], v208 offset:4096
	s_add_u32 m0, s14, 0x800
	v_mfma_f32_32x32x16_bf16 v[64:79], v[162:165], v[136:139], v[64:79]
	global_load_lds_dwordx4 v222, s[22:23]
	s_add_u32 m0, s14, 0x8800
	v_mfma_f32_32x32x16_bf16 v[80:95], v[166:169], v[136:139], v[80:95]
	global_load_lds_dwordx4 v232, s[24:25]
	ds_read_b128 v[136:139], v208 offset:8192
	s_add_u32 m0, s14, 0xc00
	v_mfma_f32_32x32x16_bf16 v[96:111], v[162:165], v[140:143], v[96:111]
	global_load_lds_dwordx4 v223, s[22:23]
	s_add_u32 m0, s14, 0x8c00
	v_mfma_f32_32x32x16_bf16 v[112:127], v[166:169], v[140:143], v[112:127]
	global_load_lds_dwordx4 v233, s[24:25]
	ds_read_b128 v[140:143], v208 offset:12288
	ds_read_b128 v[162:165], v216
	ds_read_b128 v[166:169], v216 offset:4096
	v_mfma_f32_32x32x16_bf16 v[0:15], v[170:173], v[144:147], v[0:15]
	v_mfma_f32_32x32x16_bf16 v[16:31], v[174:177], v[144:147], v[16:31]
	ds_read_b128 v[144:147], v209
	v_mfma_f32_32x32x16_bf16 v[32:47], v[170:173], v[148:151], v[32:47]
	v_mfma_f32_32x32x16_bf16 v[48:63], v[174:177], v[148:151], v[48:63]
	ds_read_b128 v[148:151], v209 offset:4096
	v_mfma_f32_32x32x16_bf16 v[64:79], v[170:173], v[152:155], v[64:79]
	v_mfma_f32_32x32x16_bf16 v[80:95], v[174:177], v[152:155], v[80:95]
	ds_read_b128 v[152:155], v209 offset:8192
	v_mfma_f32_32x32x16_bf16 v[96:111], v[170:173], v[156:159], v[96:111]
	v_mfma_f32_32x32x16_bf16 v[112:127], v[174:177], v[156:159], v[112:127]
	ds_read_b128 v[156:159], v209 offset:12288
	ds_read_b128 v[170:173], v217
	ds_read_b128 v[174:177], v217 offset:4096
	s_add_u32 s22, s22, 0x80
	s_addc_u32 s23, s23, 0
	s_add_u32 s24, s24, 0x80
	s_addc_u32 s25, s25, 0
	s_add_u32 s26, s26, 1
	s_cmp_eq_u32 s26, s20
	s_cbranch_scc0 .Lqk3_cadv_done
	s_mov_b32 s26, 0
	s_add_u32 s27, s27, s30
	s_cmp_lt_u32 s27, 0x70
	s_cbranch_scc1 .Lqk3_cadv_new
	s_lshl_b32 s34, s20, 7
	s_sub_u32 s22, s22, s34
	s_subb_u32 s23, s23, 0
	s_sub_u32 s24, s24, s34
	s_subb_u32 s25, s25, 0
	s_branch .Lqk3_cadv_done

; #define RAWBAR() { asm volatile("s_waitcnt vmcnt(0) lgkmcnt(0)" ::: "memory"); __builtin_amdgcn_s_barrier(); }
;     ...
;   if (V != 1) GLDS(0, 0);
;   RAWBAR();
;   for (int kt = 0; kt < nk; kt += 2) {
;     if (V != 1) GLDS(kt + 1, 1);
;     if (V != 2) COMPUTE(0);
;     RAWBAR();
;     if (V != 1) if (kt + 2 < nk) GLDS(kt + 2, 0);
;     if (V != 2) COMPUTE(1);
;     RAWBAR();
;   }
.Lqk3_cadv_done:
	s_waitcnt lgkmcnt(6)
	v_mfma_f32_32x32x16_bf16 v[0:15], v[162:165], v[128:131], v[0:15]
	v_mfma_f32_32x32x16_bf16 v[16:31], v[166:169], v[128:131], v[16:31]
	ds_read_b128 v[128:131], v210
	v_mfma_f32_32x32x16_bf16 v[32:47], v[162:165], v[132:135], v[32:47]
	v_mfma_f32_32x32x16_bf16 v[48:63], v[166:169], v[132:135], v[48:63]
	ds_read_b128 v[132:135], v210 offset:4096
	v_mfma_f32_32x32x16_bf16 v[64:79], v[162:165], v[136:139], v[64:79]
	v_mfma_f32_32x32x16_bf16 v[80:95], v[166:169], v[136:139], v[80:95]
	ds_read_b128 v[136:139], v210 offset:8192
	v_mfma_f32_32x32x16_bf16 v[96:111], v[162:165], v[140:143], v[96:111]
	v_mfma_f32_32x32x16_bf16 v[112:127], v[166:169], v[140:143], v[112:127]
	ds_read_b128 v[140:143], v210 offset:12288
	ds_read_b128 v[162:165], v218
	ds_read_b128 v[166:169], v218 offset:4096
	s_waitcnt lgkmcnt(6)
	v_mfma_f32_32x32x16_bf16 v[0:15], v[170:173], v[144:147], v[0:15]
	v_mfma_f32_32x32x16_bf16 v[16:31], v[174:177], v[144:147], v[16:31]
	ds_read_b128 v[144:147], v211
	v_mfma_f32_32x32x16_bf16 v[32:47], v[170:173], v[148:151], v[32:47]
	v_mfma_f32_32x32x16_bf16 v[48:63], v[174:177], v[148:151], v[48:63]
	ds_read_b128 v[148:151], v211 offset:4096
	v_mfma_f32_32x32x16_bf16 v[64:79], v[170:173], v[152:155], v[64:79]
	v_mfma_f32_32x32x16_bf16 v[80:95], v[174:177], v[152:155], v[80:95]
	ds_read_b128 v[152:155], v211 offset:8192
	v_mfma_f32_32x32x16_bf16 v[96:111], v[170:173], v[156:159], v[96:111]
	v_mfma_f32_32x32x16_bf16 v[112:127], v[174:177], v[156:159], v[112:127]
	ds_read_b128 v[156:159], v211 offset:12288
	ds_read_b128 v[170:173], v219
	ds_read_b128 v[174:177], v219 offset:4096
	s_waitcnt vmcnt(0) lgkmcnt(0)
	s_barrier
	s_add_u32 m0, s14, 0x10000
	v_mfma_f32_32x32x16_bf16 v[0:15], v[162:165], v[128:131], v[0:15]
	global_load_lds_dwordx4 v220, s[22:23]
	s_add_u32 m0, s14, 0x18000
	v_mfma_f32_32x32x16_bf16 v[16:31], v[166:169], v[128:131], v[16:31]
	global_load_lds_dwordx4 v230, s[24:25]
	ds_read_b128 v[128:131], v204
	s_add_u32 m0, s14, 0x10400
	v_mfma_f32_32x32x16_bf16 v[32:47], v[162:165], v[132:135], v[32:47]
	global_load_lds_dwordx4 v221, s[22:23]
	s_add_u32 m0, s14, 0x18400
	v_mfma_f32_32x32x16_bf16 v[48:63], v[166:169], v[132:135], v[48:63]
	global_load_lds_dwordx4 v231, s[24:25]
	ds_read_b128 v[132:135], v204 offset:4096
	s_add_u32 m0, s14, 0x10800
	v_mfma_f32_32x32x16_bf16 v[64:79], v[162:165], v[136:139], v[64:79]
	global_load_lds_dwordx4 v222, s[22:23]
	s_add_u32 m0, s14, 0x18800
	v_mfma_f32_32x32x16_bf16 v[80:95], v[166:169], v[136:139], v[80:95]
	global_load_lds_dwordx4 v232, s[24:25]
	ds_read_b128 v[136:139], v204 offset:8192
	s_add_u32 m0, s14, 0x10c00
	v_mfma_f32_32x32x16_bf16 v[96:111], v[162:165], v[140:143], v[96:111]
	global_load_lds_dwordx4 v223, s[22:23]
	s_add_u32 m0, s14, 0x18c00
	v_mfma_f32_32x32x16_bf16 v[112:127], v[166:169], v[140:143], v[112:127]
	global_load_lds_dwordx4 v233, s[24:25]
	ds_read_b128 v[140:143], v204 offset:12288
	ds_read_b128 v[162:165], v212
	ds_read_b128 v[166:169], v212 offset:4096
	v_mfma_f32_32x32x16_bf16 v[0:15], v[170:173], v[144:147], v[0:15]
	v_mfma_f32_32x32x16_bf16 v[16:31], v[174:177], v[144:147], v[16:31]
	ds_read_b128 v[144:147], v205
	v_mfma_f32_32x32x16_bf16 v[32:47], v[170:173], v[148:151], v[32:47]
	v_mfma_f32_32x32x16_bf16 v[48:63], v[174:177], v[148:151], v[48:63]
	ds_read_b128 v[148:151], v205 offset:4096
	v_mfma_f32_32x32x16_bf16 v[64:79], v[170:173], v[152:155], v[64:79]
	v_mfma_f32_32x32x16_bf16 v[80:95], v[174:177], v[152:155], v[80:95]
	ds_read_b128 v[152:155], v205 offset:8192
	v_mfma_f32_32x32x16_bf16 v[96:111], v[170:173], v[156:159], v[96:111]
	v_mfma_f32_32x32x16_bf16 v[112:127], v[174:177], v[156:159], v[112:127]
	ds_read_b128 v[156:159], v205 offset:12288
	ds_read_b128 v[170:173], v213
	ds_read_b128 v[174:177], v213 offset:4096
	s_add_u32 s22, s22, 0x80
	s_addc_u32 s23, s23, 0
	s_add_u32 s24, s24, 0x80
	s_addc_u32 s25, s25, 0
	s_add_u32 s26, s26, 1
	s_cmp_eq_u32 s26, s20
	s_cbranch_scc0 .Lqk4_cadv_done
	s_mov_b32 s26, 0
	s_add_u32 s27, s27, s30
	s_cmp_lt_u32 s27, 0x70
	s_cbranch_scc1 .Lqk4_cadv_new
	s_lshl_b32 s34, s20, 7
	s_sub_u32 s22, s22, s34
	s_subb_u32 s23, s23, 0
	s_sub_u32 s24, s24, s34
	s_subb_u32 s25, s25, 0
	s_branch .Lqk4_cadv_done

; #define RAWBAR() { asm volatile("s_waitcnt vmcnt(0) lgkmcnt(0)" ::: "memory"); __builtin_amdgcn_s_barrier(); }
;     ...
;   if (V != 1) GLDS(0, 0);
;   RAWBAR();
;   for (int kt = 0; kt < nk; kt += 2) {
;     if (V != 1) GLDS(kt + 1, 1);
;     if (V != 2) COMPUTE(0);
;     RAWBAR();
;     if (V != 1) if (kt + 2 < nk) GLDS(kt + 2, 0);
;     if (V != 2) COMPUTE(1);
;     RAWBAR();
;   }
.Lqk4_cadv_done:
	s_mov_b32 s51, s63
	s_cmp_eq_u32 s51, 0
	s_cbranch_scc1 .Lqk_pairs_done
.Lqk_pair:
	s_waitcnt lgkmcnt(6)
	v_mfma_f32_32x32x16_bf16 v[0:15], v[162:165], v[128:131], v[0:15]
	v_mfma_f32_32x32x16_bf16 v[16:31], v[166:169], v[128:131], v[16:31]
	ds_read_b128 v[128:131], v206
	v_mfma_f32_32x32x16_bf16 v[32:47], v[162:165], v[132:135], v[32:47]
	v_mfma_f32_32x32x16_bf16 v[48:63], v[166:169], v[132:135], v[48:63]
	ds_read_b128 v[132:135], v206 offset:4096
	v_mfma_f32_32x32x16_bf16 v[64:79], v[162:165], v[136:139], v[64:79]
	v_mfma_f32_32x32x16_bf16 v[80:95], v[166:169], v[136:139], v[80:95]
	ds_read_b128 v[136:139], v206 offset:8192
	v_mfma_f32_32x32x16_bf16 v[96:111], v[162:165], v[140:143], v[96:111]
	v_mfma_f32_32x32x16_bf16 v[112:127], v[166:169], v[140:143], v[112:127]
	ds_read_b128 v[140:143], v206 offset:12288
	ds_read_b128 v[162:165], v214
	ds_read_b128 v[166:169], v214 offset:4096
	s_waitcnt lgkmcnt(6)
	v_mfma_f32_32x32x16_bf16 v[0:15], v[170:173], v[144:147], v[0:15]
	v_mfma_f32_32x32x16_bf16 v[16:31], v[174:177], v[144:147], v[16:31]
	ds_read_b128 v[144:147], v207
	v_mfma_f32_32x32x16_bf16 v[32:47], v[170:173], v[148:151], v[32:47]
	v_mfma_f32_32x32x16_bf16 v[48:63], v[174:177], v[148:151], v[48:63]
	ds_read_b128 v[148:151], v207 offset:4096
	v_mfma_f32_32x32x16_bf16 v[64:79], v[170:173], v[152:155], v[64:79]
	v_mfma_f32_32x32x16_bf16 v[80:95], v[174:177], v[152:155], v[80:95]
	ds_read_b128 v[152:155], v207 offset:8192
	v_mfma_f32_32x32x16_bf16 v[96:111], v[170:173], v[156:159], v[96:111]
	v_mfma_f32_32x32x16_bf16 v[112:127], v[174:177], v[156:159], v[112:127]
	ds_read_b128 v[156:159], v207 offset:12288
	ds_read_b128 v[170:173], v215
	ds_read_b128 v[174:177], v215 offset:4096
	s_waitcnt vmcnt(0) lgkmcnt(0)
	s_barrier
	s_add_u32 m0, s14, 0x0
	v_mfma_f32_32x32x16_bf16 v[0:15], v[162:165], v[128:131], v[0:15]
	global_load_lds_dwordx4 v220, s[22:23]
	s_add_u32 m0, s14, 0x8000
	v_mfma_f32_32x32x16_bf16 v[16:31], v[166:169], v[128:131], v[16:31]
	global_load_lds_dwordx4 v230, s[24:25]
	ds_read_b128 v[128:131], v208
	s_add_u32 m0, s14, 0x400
	v_mfma_f32_32x32x16_bf16 v[32:47], v[162:165], v[132:135], v[32:47]
	global_load_lds_dwordx4 v221, s[22:23]
	s_add_u32 m0, s14, 0x8400
	v_mfma_f32_32x32x16_bf16 v[48:63], v[166:169], v[132:135], v[48:63]
	global_load_lds_dwordx4 v231, s[24:25]
	ds_read_b128 v[132:135], v208 offset:4096
	s_add_u32 m0, s14, 0x800
	v_mfma_f32_32x32x16_bf16 v[64:79], v[162:165], v[136:139], v[64:79]
	global_load_lds_dwordx4 v222, s[22:23]
	s_add_u32 m0, s14, 0x8800
	v_mfma_f32_32x32x16_bf16 v[80:95], v[166:169], v[136:139], v[80:95]
	global_load_lds_dwordx4 v232, s[24:25]
	ds_read_b128 v[136:139], v208 offset:8192
	s_add_u32 m0, s14, 0xc00
	v_mfma_f32_32x32x16_bf16 v[96:111], v[162:165], v[140:143], v[96:111]
	global_load_lds_dwordx4 v223, s[22:23]
	s_add_u32 m0, s14, 0x8c00
	v_mfma_f32_32x32x16_bf16 v[112:127], v[166:169], v[140:143], v[112:127]
	global_load_lds_dwordx4 v233, s[24:25]
	ds_read_b128 v[140:143], v208 offset:12288
	ds_read_b128 v[162:165], v216
	ds_read_b128 v[166:169], v216 offset:4096
	v_mfma_f32_32x32x16_bf16 v[0:15], v[170:173], v[144:147], v[0:15]
	v_mfma_f32_32x32x16_bf16 v[16:31], v[174:177], v[144:147], v[16:31]
	ds_read_b128 v[144:147], v209
	v_mfma_f32_32x32x16_bf16 v[32:47], v[170:173], v[148:151], v[32:47]
	v_mfma_f32_32x32x16_bf16 v[48:63], v[174:177], v[148:151], v[48:63]
	ds_read_b128 v[148:151], v209 offset:4096
	v_mfma_f32_32x32x16_bf16 v[64:79], v[170:173], v[152:155], v[64:79]
	v_mfma_f32_32x32x16_bf16 v[80:95], v[174:177], v[152:155], v[80:95]
	ds_read_b128 v[152:155], v209 offset:8192
	v_mfma_f32_32x32x16_bf16 v[96:111], v[170:173], v[156:159], v[96:111]
	v_mfma_f32_32x32x16_bf16 v[112:127], v[174:177], v[156:159], v[112:127]
	ds_read_b128 v[156:159], v209 offset:12288
	ds_read_b128 v[170:173], v217
	ds_read_b128 v[174:177], v217 offset:4096
	s_add_u32 s22, s22, 0x80
	s_addc_u32 s23, s23, 0
	s_add_u32 s24, s24, 0x80
	s_addc_u32 s25, s25, 0
	s_add_u32 s26, s26, 1
	s_cmp_eq_u32 s26, s20
	s_cbranch_scc0 .Lqk5_cadv_done
	s_mov_b32 s26, 0
	s_add_u32 s27, s27, s30
	s_cmp_lt_u32 s27, 0x70
	s_cbranch_scc1 .Lqk5_cadv_new
	s_lshl_b32 s34, s20, 7
	s_sub_u32 s22, s22, s34
	s_subb_u32 s23, s23, 0
	s_sub_u32 s24, s24, s34
	s_subb_u32 s25, s25, 0
	s_branch .Lqk5_cadv_done

; #define RAWBAR() { asm volatile("s_waitcnt vmcnt(0) lgkmcnt(0)" ::: "memory"); __builtin_amdgcn_s_barrier(); }
;     ...
;   for (int kt = 0; kt < nk; kt += 2) {
;     if (V != 1) GLDS(kt + 1, 1);
;     if (V != 2) COMPUTE(0);
;     RAWBAR();
;     if (V != 1) if (kt + 2 < nk) GLDS(kt + 2, 0);
;     if (V != 2) COMPUTE(1);
;     RAWBAR();
;   }
.Lqk6_cadv_done:
	s_sub_u32 s51, s51, 1
	s_cmp_lg_u32 s51, 0
	s_cbranch_scc1 .Lqk_pair

; DI float bf2f(unsigned h) { return __uint_as_float(h << 16); }
; #define RAWBAR() { asm volatile("s_waitcnt vmcnt(0) lgkmcnt(0)" ::: "memory"); __builtin_amdgcn_s_barrier(); }
;     ...
;   if (V != 1) GLDS(0, 0);
;   RAWBAR();
;   for (int kt = 0; kt < nk; kt += 2) {
;     if (V != 1) GLDS(kt + 1, 1);
;     if (V != 2) COMPUTE(0);
;     RAWBAR();
;     if (V != 1) if (kt + 2 < nk) GLDS(kt + 2, 0);
;     if (V != 2) COMPUTE(1);
;     RAWBAR();
;   }
; DI void qkv_phase(const Params& p, int j, char* smem) {
;     ...
;     {
;       const int row = tid >> 1, half = tid & 1, nh = ncols / 2;
;       const u16* src = zc + (size_t)(m0 + row) * 640 + coff + half * nh;
;       float s = 0.f;
;       for (int c = 0; c < nh; c += 8) {
;         const uint4 v = *(const uint4*)(src + c);
;         float f;
;         f = bf2f(v.x & 0xffffu); s += f * f; f = bf2f(v.x >> 16); s += f * f;
;         f = bf2f(v.y & 0xffffu); s += f * f; f = bf2f(v.y >> 16); s += f * f;
;         f = bf2f(v.z & 0xffffu); s += f * f; f = bf2f(v.z >> 16); s += f * f;
;         f = bf2f(v.w & 0xffffu); s += f * f; f = bf2f(v.w >> 16); s += f * f;
;       }
.Lqk7_cadv_done:
	s_waitcnt lgkmcnt(6)
	v_mfma_f32_32x32x16_bf16 v[0:15], v[162:165], v[128:131], v[0:15]
	v_mfma_f32_32x32x16_bf16 v[16:31], v[166:169], v[128:131], v[16:31]
	ds_read_b128 v[128:131], v210
	v_mfma_f32_32x32x16_bf16 v[32:47], v[162:165], v[132:135], v[32:47]
	v_mfma_f32_32x32x16_bf16 v[48:63], v[166:169], v[132:135], v[48:63]
	ds_read_b128 v[132:135], v210 offset:4096
	v_mfma_f32_32x32x16_bf16 v[64:79], v[162:165], v[136:139], v[64:79]
	v_mfma_f32_32x32x16_bf16 v[80:95], v[166:169], v[136:139], v[80:95]
	ds_read_b128 v[136:139], v210 offset:8192
	v_mfma_f32_32x32x16_bf16 v[96:111], v[162:165], v[140:143], v[96:111]
	v_mfma_f32_32x32x16_bf16 v[112:127], v[166:169], v[140:143], v[112:127]
	ds_read_b128 v[140:143], v210 offset:12288
	ds_read_b128 v[162:165], v218
	ds_read_b128 v[166:169], v218 offset:4096
	s_waitcnt lgkmcnt(6)
	v_mfma_f32_32x32x16_bf16 v[0:15], v[170:173], v[144:147], v[0:15]
	v_mfma_f32_32x32x16_bf16 v[16:31], v[174:177], v[144:147], v[16:31]
	ds_read_b128 v[144:147], v211
	v_mfma_f32_32x32x16_bf16 v[32:47], v[170:173], v[148:151], v[32:47]
	v_mfma_f32_32x32x16_bf16 v[48:63], v[174:177], v[148:151], v[48:63]
	ds_read_b128 v[148:151], v211 offset:4096
	v_mfma_f32_32x32x16_bf16 v[64:79], v[170:173], v[152:155], v[64:79]
	v_mfma_f32_32x32x16_bf16 v[80:95], v[174:177], v[152:155], v[80:95]
	ds_read_b128 v[152:155], v211 offset:8192
	v_mfma_f32_32x32x16_bf16 v[96:111], v[170:173], v[156:159], v[96:111]
	v_mfma_f32_32x32x16_bf16 v[112:127], v[174:177], v[156:159], v[112:127]
	ds_read_b128 v[156:159], v211 offset:12288
	ds_read_b128 v[170:173], v219
	ds_read_b128 v[174:177], v219 offset:4096
	s_waitcnt vmcnt(0) lgkmcnt(0)
	s_barrier
	s_add_u32 m0, s14, 0x10000
	v_mfma_f32_32x32x16_bf16 v[0:15], v[162:165], v[128:131], v[0:15]
	global_load_lds_dwordx4 v220, s[22:23]
	s_add_u32 m0, s14, 0x10400
	v_mfma_f32_32x32x16_bf16 v[16:31], v[166:169], v[128:131], v[16:31]
	global_load_lds_dwordx4 v221, s[22:23]
	s_add_u32 m0, s14, 0x10800
	v_mfma_f32_32x32x16_bf16 v[32:47], v[162:165], v[132:135], v[32:47]
	global_load_lds_dwordx4 v222, s[22:23]
	s_add_u32 m0, s14, 0x10c00
	v_mfma_f32_32x32x16_bf16 v[48:63], v[166:169], v[132:135], v[48:63]
	global_load_lds_dwordx4 v223, s[22:23]
	v_mfma_f32_32x32x16_bf16 v[64:79], v[162:165], v[136:139], v[64:79]
	v_mfma_f32_32x32x16_bf16 v[80:95], v[166:169], v[136:139], v[80:95]
	v_mfma_f32_32x32x16_bf16 v[96:111], v[162:165], v[140:143], v[96:111]
	v_mfma_f32_32x32x16_bf16 v[112:127], v[166:169], v[140:143], v[112:127]
	v_mfma_f32_32x32x16_bf16 v[0:15], v[170:173], v[144:147], v[0:15]
	v_mfma_f32_32x32x16_bf16 v[16:31], v[174:177], v[144:147], v[16:31]
	v_mfma_f32_32x32x16_bf16 v[32:47], v[170:173], v[148:151], v[32:47]
	v_mfma_f32_32x32x16_bf16 v[48:63], v[174:177], v[148:151], v[48:63]
	v_mfma_f32_32x32x16_bf16 v[64:79], v[170:173], v[152:155], v[64:79]
	v_mfma_f32_32x32x16_bf16 v[80:95], v[174:177], v[152:155], v[80:95]
	v_mfma_f32_32x32x16_bf16 v[96:111], v[170:173], v[156:159], v[96:111]
	v_mfma_f32_32x32x16_bf16 v[112:127], v[174:177], v[156:159], v[112:127]
	s_lshl_b32 s56, s61, 8
	s_add_u32 s56, s56, s12
	s_mul_i32 s34, s61, 0x50000
	s_add_u32 s40, s10, s34
	s_addc_u32 s41, s11, 0
	s_cmp_eq_u32 s60, 1
	s_cselect_b32 s34, 0, 0x300
	s_movk_i32 s35, 0x100
	s_cselect_b32 s35, 0x180, s35
	s_add_u32 s40, s40, s34
	s_addc_u32 s41, s41, 0
	v_and_b32_e32 v246, 1, v182
	v_mul_u32_u24_e32 v246, s35, v246
	v_add_u32_e32 v246, v238, v246
	v_mov_b32_e32 v244, 0
	v_mov_b32_e32 v245, 0
	global_load_dwordx4 v[128:131], v246, s[40:41]
	global_load_dwordx4 v[132:135], v246, s[40:41] offset:16
	global_load_dwordx4 v[136:139], v246, s[40:41] offset:32
	global_load_dwordx4 v[140:143], v246, s[40:41] offset:48
	global_load_dwordx4 v[144:147], v246, s[40:41] offset:64
	global_load_dwordx4 v[148:151], v246, s[40:41] offset:80
	global_load_dwordx4 v[152:155], v246, s[40:41] offset:96
	global_load_dwordx4 v[156:159], v246, s[40:41] offset:112
	s_waitcnt vmcnt(7)
	v_lshlrev_b32_e32 v242, 16, v128
	v_and_b32_e32 v243, 0xffff0000, v128
	v_fmac_f32_e32 v244, v242, v242
	v_fmac_f32_e32 v245, v243, v243
	v_lshlrev_b32_e32 v242, 16, v129
	v_and_b32_e32 v243, 0xffff0000, v129
	v_fmac_f32_e32 v245, v242, v242
	v_fmac_f32_e32 v244, v243, v243
	v_lshlrev_b32_e32 v242, 16, v130
	v_and_b32_e32 v243, 0xffff0000, v130
	v_fmac_f32_e32 v244, v242, v242
	v_fmac_f32_e32 v245, v243, v243
	v_lshlrev_b32_e32 v242, 16, v131
	v_and_b32_e32 v243, 0xffff0000, v131
	v_fmac_f32_e32 v245, v242, v242
	v_fmac_f32_e32 v244, v243, v243
	s_waitcnt vmcnt(6)
	v_lshlrev_b32_e32 v242, 16, v132
	v_and_b32_e32 v243, 0xffff0000, v132
	v_fmac_f32_e32 v244, v242, v242
	v_fmac_f32_e32 v245, v243, v243
	v_lshlrev_b32_e32 v242, 16, v133
	v_and_b32_e32 v243, 0xffff0000, v133
	v_fmac_f32_e32 v245, v242, v242
	v_fmac_f32_e32 v244, v243, v243
	v_lshlrev_b32_e32 v242, 16, v134
	v_and_b32_e32 v243, 0xffff0000, v134
	v_fmac_f32_e32 v244, v242, v242
	v_fmac_f32_e32 v245, v243, v243
	v_lshlrev_b32_e32 v242, 16, v135
	v_and_b32_e32 v243, 0xffff0000, v135
	v_fmac_f32_e32 v245, v242, v242
	v_fmac_f32_e32 v244, v243, v243
	s_waitcnt vmcnt(5)
	v_lshlrev_b32_e32 v242, 16, v136
	v_and_b32_e32 v243, 0xffff0000, v136
	v_fmac_f32_e32 v244, v242, v242
	v_fmac_f32_e32 v245, v243, v243
	v_lshlrev_b32_e32 v242, 16, v137
	v_and_b32_e32 v243, 0xffff0000, v137
	v_fmac_f32_e32 v245, v242, v242
	v_fmac_f32_e32 v244, v243, v243
	v_lshlrev_b32_e32 v242, 16, v138
	v_and_b32_e32 v243, 0xffff0000, v138
	v_fmac_f32_e32 v244, v242, v242
	v_fmac_f32_e32 v245, v243, v243
	v_lshlrev_b32_e32 v242, 16, v139
	v_and_b32_e32 v243, 0xffff0000, v139
	v_fmac_f32_e32 v245, v242, v242
	v_fmac_f32_e32 v244, v243, v243
	s_waitcnt vmcnt(4)
; DI float bf2f(unsigned h) { return __uint_as_float(h << 16); }
; DI void qkv_phase(const Params& p, int j, char* smem) {
;     ...
;       const int row = tid >> 1, half = tid & 1, nh = ncols / 2;
;       const u16* src = zc + (size_t)(m0 + row) * 640 + coff + half * nh;
;       float s = 0.f;
;       for (int c = 0; c < nh; c += 8) {
;         const uint4 v = *(const uint4*)(src + c);
;         float f;
;         f = bf2f(v.x & 0xffffu); s += f * f; f = bf2f(v.x >> 16); s += f * f;
;         f = bf2f(v.y & 0xffffu); s += f * f; f = bf2f(v.y >> 16); s += f * f;
;         f = bf2f(v.z & 0xffffu); s += f * f; f = bf2f(v.z >> 16); s += f * f;
;         f = bf2f(v.w & 0xffffu); s += f * f; f = bf2f(v.w >> 16); s += f * f;
;       }
	v_lshlrev_b32_e32 v242, 16, v140
	v_and_b32_e32 v243, 0xffff0000, v140
	v_fmac_f32_e32 v244, v242, v242
	v_fmac_f32_e32 v245, v243, v243
	v_lshlrev_b32_e32 v242, 16, v141
	v_and_b32_e32 v243, 0xffff0000, v141
	v_fmac_f32_e32 v245, v242, v242
	v_fmac_f32_e32 v244, v243, v243
	v_lshlrev_b32_e32 v242, 16, v142
	v_and_b32_e32 v243, 0xffff0000, v142
	v_fmac_f32_e32 v244, v242, v242
	v_fmac_f32_e32 v245, v243, v243
	v_lshlrev_b32_e32 v242, 16, v143
	v_and_b32_e32 v243, 0xffff0000, v143
	v_fmac_f32_e32 v245, v242, v242
	v_fmac_f32_e32 v244, v243, v243
	s_waitcnt vmcnt(3)
	v_lshlrev_b32_e32 v242, 16, v144
	v_and_b32_e32 v243, 0xffff0000, v144
	v_fmac_f32_e32 v244, v242, v242
	v_fmac_f32_e32 v245, v243, v243
	v_lshlrev_b32_e32 v242, 16, v145
	v_and_b32_e32 v243, 0xffff0000, v145
	v_fmac_f32_e32 v245, v242, v242
	v_fmac_f32_e32 v244, v243, v243
	v_lshlrev_b32_e32 v242, 16, v146
	v_and_b32_e32 v243, 0xffff0000, v146
	v_fmac_f32_e32 v244, v242, v242
	v_fmac_f32_e32 v245, v243, v243
	v_lshlrev_b32_e32 v242, 16, v147
	v_and_b32_e32 v243, 0xffff0000, v147
	v_fmac_f32_e32 v245, v242, v242
	v_fmac_f32_e32 v244, v243, v243
	s_waitcnt vmcnt(2)
	v_lshlrev_b32_e32 v242, 16, v148
	v_and_b32_e32 v243, 0xffff0000, v148
	v_fmac_f32_e32 v244, v242, v242
	v_fmac_f32_e32 v245, v243, v243
	v_lshlrev_b32_e32 v242, 16, v149
	v_and_b32_e32 v243, 0xffff0000, v149
	v_fmac_f32_e32 v245, v242, v242
	v_fmac_f32_e32 v244, v243, v243
	v_lshlrev_b32_e32 v242, 16, v150
	v_and_b32_e32 v243, 0xffff0000, v150
	v_fmac_f32_e32 v244, v242, v242
	v_fmac_f32_e32 v245, v243, v243
	v_lshlrev_b32_e32 v242, 16, v151
	v_and_b32_e32 v243, 0xffff0000, v151
	v_fmac_f32_e32 v245, v242, v242
	v_fmac_f32_e32 v244, v243, v243
	s_waitcnt vmcnt(1)
	v_lshlrev_b32_e32 v242, 16, v152
	v_and_b32_e32 v243, 0xffff0000, v152
	v_fmac_f32_e32 v244, v242, v242
	v_fmac_f32_e32 v245, v243, v243
	v_lshlrev_b32_e32 v242, 16, v153
	v_and_b32_e32 v243, 0xffff0000, v153
	v_fmac_f32_e32 v245, v242, v242
	v_fmac_f32_e32 v244, v243, v243
	v_lshlrev_b32_e32 v242, 16, v154
	v_and_b32_e32 v243, 0xffff0000, v154
	v_fmac_f32_e32 v244, v242, v242
	v_fmac_f32_e32 v245, v243, v243
	v_lshlrev_b32_e32 v242, 16, v155
	v_and_b32_e32 v243, 0xffff0000, v155
	v_fmac_f32_e32 v245, v242, v242
	v_fmac_f32_e32 v244, v243, v243
	s_waitcnt vmcnt(0)
	v_lshlrev_b32_e32 v242, 16, v156
	v_and_b32_e32 v243, 0xffff0000, v156
	v_fmac_f32_e32 v244, v242, v242
	v_fmac_f32_e32 v245, v243, v243
	v_lshlrev_b32_e32 v242, 16, v157
	v_and_b32_e32 v243, 0xffff0000, v157
	v_fmac_f32_e32 v245, v242, v242
	v_fmac_f32_e32 v244, v243, v243
	v_lshlrev_b32_e32 v242, 16, v158
	v_and_b32_e32 v243, 0xffff0000, v158
	v_fmac_f32_e32 v244, v242, v242
	v_fmac_f32_e32 v245, v243, v243
	v_lshlrev_b32_e32 v242, 16, v159
	v_and_b32_e32 v243, 0xffff0000, v159
	v_fmac_f32_e32 v245, v242, v242
	v_fmac_f32_e32 v244, v243, v243
	global_load_dwordx4 v[128:131], v246, s[40:41] offset:128
	global_load_dwordx4 v[132:135], v246, s[40:41] offset:144
	global_load_dwordx4 v[136:139], v246, s[40:41] offset:160
	global_load_dwordx4 v[140:143], v246, s[40:41] offset:176
	global_load_dwordx4 v[144:147], v246, s[40:41] offset:192
	global_load_dwordx4 v[148:151], v246, s[40:41] offset:208
	global_load_dwordx4 v[152:155], v246, s[40:41] offset:224
	global_load_dwordx4 v[156:159], v246, s[40:41] offset:240
	s_waitcnt vmcnt(7)
	v_lshlrev_b32_e32 v242, 16, v128
	v_and_b32_e32 v243, 0xffff0000, v128
	v_fmac_f32_e32 v244, v242, v242
	v_fmac_f32_e32 v245, v243, v243
	v_lshlrev_b32_e32 v242, 16, v129
	v_and_b32_e32 v243, 0xffff0000, v129
	v_fmac_f32_e32 v245, v242, v242
	v_fmac_f32_e32 v244, v243, v243
	v_lshlrev_b32_e32 v242, 16, v130
	v_and_b32_e32 v243, 0xffff0000, v130
	v_fmac_f32_e32 v244, v242, v242
	v_fmac_f32_e32 v245, v243, v243
	v_lshlrev_b32_e32 v242, 16, v131
	v_and_b32_e32 v243, 0xffff0000, v131
	v_fmac_f32_e32 v245, v242, v242
	v_fmac_f32_e32 v244, v243, v243
	s_waitcnt vmcnt(6)
	v_lshlrev_b32_e32 v242, 16, v132
	v_and_b32_e32 v243, 0xffff0000, v132
	v_fmac_f32_e32 v244, v242, v242
	v_fmac_f32_e32 v245, v243, v243
	v_lshlrev_b32_e32 v242, 16, v133
	v_and_b32_e32 v243, 0xffff0000, v133
	v_fmac_f32_e32 v245, v242, v242
	v_fmac_f32_e32 v244, v243, v243
	v_lshlrev_b32_e32 v242, 16, v134
	v_and_b32_e32 v243, 0xffff0000, v134
	v_fmac_f32_e32 v244, v242, v242
	v_fmac_f32_e32 v245, v243, v243
	v_lshlrev_b32_e32 v242, 16, v135
	v_and_b32_e32 v243, 0xffff0000, v135
	v_fmac_f32_e32 v245, v242, v242
	v_fmac_f32_e32 v244, v243, v243
	s_waitcnt vmcnt(5)
	v_lshlrev_b32_e32 v242, 16, v136
	v_and_b32_e32 v243, 0xffff0000, v136
	v_fmac_f32_e32 v244, v242, v242
	v_fmac_f32_e32 v245, v243, v243
	v_lshlrev_b32_e32 v242, 16, v137
	v_and_b32_e32 v243, 0xffff0000, v137
	v_fmac_f32_e32 v245, v242, v242
	v_fmac_f32_e32 v244, v243, v243
	v_lshlrev_b32_e32 v242, 16, v138
	v_and_b32_e32 v243, 0xffff0000, v138
	v_fmac_f32_e32 v244, v242, v242
	v_fmac_f32_e32 v245, v243, v243
	v_lshlrev_b32_e32 v242, 16, v139
	v_and_b32_e32 v243, 0xffff0000, v139
	v_fmac_f32_e32 v245, v242, v242
	v_fmac_f32_e32 v244, v243, v243
	s_waitcnt vmcnt(4)
	v_lshlrev_b32_e32 v242, 16, v140
	v_and_b32_e32 v243, 0xffff0000, v140
	v_fmac_f32_e32 v244, v242, v242
	v_fmac_f32_e32 v245, v243, v243
	v_lshlrev_b32_e32 v242, 16, v141
	v_and_b32_e32 v243, 0xffff0000, v141
	v_fmac_f32_e32 v245, v242, v242
	v_fmac_f32_e32 v244, v243, v243
	v_lshlrev_b32_e32 v242, 16, v142
	v_and_b32_e32 v243, 0xffff0000, v142
	v_fmac_f32_e32 v244, v242, v242
	v_fmac_f32_e32 v245, v243, v243
	v_lshlrev_b32_e32 v242, 16, v143
	v_and_b32_e32 v243, 0xffff0000, v143
	v_fmac_f32_e32 v245, v242, v242
	v_fmac_f32_e32 v244, v243, v243
	s_waitcnt vmcnt(3)
; DI float bf2f(unsigned h) { return __uint_as_float(h << 16); }
; DI void qkv_phase(const Params& p, int j, char* smem) {
;     ...
;       const int row = tid >> 1, half = tid & 1, nh = ncols / 2;
;       const u16* src = zc + (size_t)(m0 + row) * 640 + coff + half * nh;
;       float s = 0.f;
;       for (int c = 0; c < nh; c += 8) {
;         const uint4 v = *(const uint4*)(src + c);
;         float f;
;         f = bf2f(v.x & 0xffffu); s += f * f; f = bf2f(v.x >> 16); s += f * f;
;         f = bf2f(v.y & 0xffffu); s += f * f; f = bf2f(v.y >> 16); s += f * f;
;         f = bf2f(v.z & 0xffffu); s += f * f; f = bf2f(v.z >> 16); s += f * f;
;         f = bf2f(v.w & 0xffffu); s += f * f; f = bf2f(v.w >> 16); s += f * f;
;       }
	v_lshlrev_b32_e32 v242, 16, v144
	v_and_b32_e32 v243, 0xffff0000, v144
	v_fmac_f32_e32 v244, v242, v242
	v_fmac_f32_e32 v245, v243, v243
	v_lshlrev_b32_e32 v242, 16, v145
	v_and_b32_e32 v243, 0xffff0000, v145
	v_fmac_f32_e32 v245, v242, v242
	v_fmac_f32_e32 v244, v243, v243
	v_lshlrev_b32_e32 v242, 16, v146
	v_and_b32_e32 v243, 0xffff0000, v146
	v_fmac_f32_e32 v244, v242, v242
	v_fmac_f32_e32 v245, v243, v243
	v_lshlrev_b32_e32 v242, 16, v147
	v_and_b32_e32 v243, 0xffff0000, v147
	v_fmac_f32_e32 v245, v242, v242
	v_fmac_f32_e32 v244, v243, v243
	s_waitcnt vmcnt(2)
	v_lshlrev_b32_e32 v242, 16, v148
	v_and_b32_e32 v243, 0xffff0000, v148
	v_fmac_f32_e32 v244, v242, v242
	v_fmac_f32_e32 v245, v243, v243
	v_lshlrev_b32_e32 v242, 16, v149
	v_and_b32_e32 v243, 0xffff0000, v149
	v_fmac_f32_e32 v245, v242, v242
	v_fmac_f32_e32 v244, v243, v243
	v_lshlrev_b32_e32 v242, 16, v150
	v_and_b32_e32 v243, 0xffff0000, v150
	v_fmac_f32_e32 v244, v242, v242
	v_fmac_f32_e32 v245, v243, v243
	v_lshlrev_b32_e32 v242, 16, v151
	v_and_b32_e32 v243, 0xffff0000, v151
	v_fmac_f32_e32 v245, v242, v242
	v_fmac_f32_e32 v244, v243, v243
	s_waitcnt vmcnt(1)
	v_lshlrev_b32_e32 v242, 16, v152
	v_and_b32_e32 v243, 0xffff0000, v152
	v_fmac_f32_e32 v244, v242, v242
	v_fmac_f32_e32 v245, v243, v243
	v_lshlrev_b32_e32 v242, 16, v153
	v_and_b32_e32 v243, 0xffff0000, v153
	v_fmac_f32_e32 v245, v242, v242
	v_fmac_f32_e32 v244, v243, v243
	v_lshlrev_b32_e32 v242, 16, v154
	v_and_b32_e32 v243, 0xffff0000, v154
	v_fmac_f32_e32 v244, v242, v242
	v_fmac_f32_e32 v245, v243, v243
	v_lshlrev_b32_e32 v242, 16, v155
	v_and_b32_e32 v243, 0xffff0000, v155
	v_fmac_f32_e32 v245, v242, v242
	v_fmac_f32_e32 v244, v243, v243
	s_waitcnt vmcnt(0)
	v_lshlrev_b32_e32 v242, 16, v156
	v_and_b32_e32 v243, 0xffff0000, v156
	v_fmac_f32_e32 v244, v242, v242
	v_fmac_f32_e32 v245, v243, v243
	v_lshlrev_b32_e32 v242, 16, v157
	v_and_b32_e32 v243, 0xffff0000, v157
	v_fmac_f32_e32 v245, v242, v242
	v_fmac_f32_e32 v244, v243, v243
	v_lshlrev_b32_e32 v242, 16, v158
	v_and_b32_e32 v243, 0xffff0000, v158
	v_fmac_f32_e32 v244, v242, v242
	v_fmac_f32_e32 v245, v243, v243
	v_lshlrev_b32_e32 v242, 16, v159
	v_and_b32_e32 v243, 0xffff0000, v159
	v_fmac_f32_e32 v245, v242, v242
	v_fmac_f32_e32 v244, v243, v243
	s_cmp_eq_u32 s60, 1
	s_cbranch_scc0 .Lqk_rs_done
	global_load_dwordx4 v[128:131], v246, s[40:41] offset:256
	global_load_dwordx4 v[132:135], v246, s[40:41] offset:272
	global_load_dwordx4 v[136:139], v246, s[40:41] offset:288
	global_load_dwordx4 v[140:143], v246, s[40:41] offset:304
	global_load_dwordx4 v[144:147], v246, s[40:41] offset:320
	global_load_dwordx4 v[148:151], v246, s[40:41] offset:336
	global_load_dwordx4 v[152:155], v246, s[40:41] offset:352
	global_load_dwordx4 v[156:159], v246, s[40:41] offset:368
	s_waitcnt vmcnt(7)
	v_lshlrev_b32_e32 v242, 16, v128
	v_and_b32_e32 v243, 0xffff0000, v128
	v_fmac_f32_e32 v244, v242, v242
	v_fmac_f32_e32 v245, v243, v243
	v_lshlrev_b32_e32 v242, 16, v129
	v_and_b32_e32 v243, 0xffff0000, v129
	v_fmac_f32_e32 v245, v242, v242
	v_fmac_f32_e32 v244, v243, v243
	v_lshlrev_b32_e32 v242, 16, v130
	v_and_b32_e32 v243, 0xffff0000, v130
	v_fmac_f32_e32 v244, v242, v242
	v_fmac_f32_e32 v245, v243, v243
	v_lshlrev_b32_e32 v242, 16, v131
	v_and_b32_e32 v243, 0xffff0000, v131
	v_fmac_f32_e32 v245, v242, v242
	v_fmac_f32_e32 v244, v243, v243
	s_waitcnt vmcnt(6)
	v_lshlrev_b32_e32 v242, 16, v132
	v_and_b32_e32 v243, 0xffff0000, v132
	v_fmac_f32_e32 v244, v242, v242
	v_fmac_f32_e32 v245, v243, v243
	v_lshlrev_b32_e32 v242, 16, v133
	v_and_b32_e32 v243, 0xffff0000, v133
	v_fmac_f32_e32 v245, v242, v242
	v_fmac_f32_e32 v244, v243, v243
	v_lshlrev_b32_e32 v242, 16, v134
	v_and_b32_e32 v243, 0xffff0000, v134
	v_fmac_f32_e32 v244, v242, v242
	v_fmac_f32_e32 v245, v243, v243
	v_lshlrev_b32_e32 v242, 16, v135
	v_and_b32_e32 v243, 0xffff0000, v135
	v_fmac_f32_e32 v245, v242, v242
	v_fmac_f32_e32 v244, v243, v243
	s_waitcnt vmcnt(5)
	v_lshlrev_b32_e32 v242, 16, v136
	v_and_b32_e32 v243, 0xffff0000, v136
	v_fmac_f32_e32 v244, v242, v242
	v_fmac_f32_e32 v245, v243, v243
	v_lshlrev_b32_e32 v242, 16, v137
	v_and_b32_e32 v243, 0xffff0000, v137
	v_fmac_f32_e32 v245, v242, v242
	v_fmac_f32_e32 v244, v243, v243
	v_lshlrev_b32_e32 v242, 16, v138
	v_and_b32_e32 v243, 0xffff0000, v138
	v_fmac_f32_e32 v244, v242, v242
	v_fmac_f32_e32 v245, v243, v243
	v_lshlrev_b32_e32 v242, 16, v139
	v_and_b32_e32 v243, 0xffff0000, v139
	v_fmac_f32_e32 v245, v242, v242
	v_fmac_f32_e32 v244, v243, v243
	s_waitcnt vmcnt(4)
	v_lshlrev_b32_e32 v242, 16, v140
	v_and_b32_e32 v243, 0xffff0000, v140
	v_fmac_f32_e32 v244, v242, v242
	v_fmac_f32_e32 v245, v243, v243
	v_lshlrev_b32_e32 v242, 16, v141
	v_and_b32_e32 v243, 0xffff0000, v141
	v_fmac_f32_e32 v245, v242, v242
	v_fmac_f32_e32 v244, v243, v243
	v_lshlrev_b32_e32 v242, 16, v142
	v_and_b32_e32 v243, 0xffff0000, v142
	v_fmac_f32_e32 v244, v242, v242
	v_fmac_f32_e32 v245, v243, v243
	v_lshlrev_b32_e32 v242, 16, v143
	v_and_b32_e32 v243, 0xffff0000, v143
	v_fmac_f32_e32 v245, v242, v242
	v_fmac_f32_e32 v244, v243, v243
	s_waitcnt vmcnt(3)
	v_lshlrev_b32_e32 v242, 16, v144
	v_and_b32_e32 v243, 0xffff0000, v144
	v_fmac_f32_e32 v244, v242, v242
	v_fmac_f32_e32 v245, v243, v243
	v_lshlrev_b32_e32 v242, 16, v145
	v_and_b32_e32 v243, 0xffff0000, v145
	v_fmac_f32_e32 v245, v242, v242
	v_fmac_f32_e32 v244, v243, v243
	v_lshlrev_b32_e32 v242, 16, v146
	v_and_b32_e32 v243, 0xffff0000, v146
	v_fmac_f32_e32 v244, v242, v242
	v_fmac_f32_e32 v245, v243, v243
	v_lshlrev_b32_e32 v242, 16, v147
	v_and_b32_e32 v243, 0xffff0000, v147
	v_fmac_f32_e32 v245, v242, v242
	v_fmac_f32_e32 v244, v243, v243
	s_waitcnt vmcnt(2)
; DI int crow(int r, int hf) { return (r & 3) + 8 * (r >> 2) + 4 * hf; }
; DI void qkv_phase(const Params& p, int j, char* smem) {
;     ...
;       s += __shfl_xor(s, 1);
;       if (half == 0) rsc[row] = rsqrtf(s / (float)ncols + 1e-6f);
;     }
;     __syncthreads();
;     ...
;             for (int r = 0; r < 16; ++r) {
;               const int rr = rl + crow(r, hf_), t = m0_ + rr;
;               const float x = acc[i][jn][r] * rsc[moff + rr] * MLA_QSCALE;
;               if (C64 < 512) {
;                 Qb[(size_t)t * 768 + (C64 >> 6) * 96 + jn * 32 + l32_] = f2bf(x);
	v_lshlrev_b32_e32 v242, 16, v148
	v_and_b32_e32 v243, 0xffff0000, v148
	v_fmac_f32_e32 v244, v242, v242
	v_fmac_f32_e32 v245, v243, v243
	v_lshlrev_b32_e32 v242, 16, v149
	v_and_b32_e32 v243, 0xffff0000, v149
	v_fmac_f32_e32 v245, v242, v242
	v_fmac_f32_e32 v244, v243, v243
	v_lshlrev_b32_e32 v242, 16, v150
	v_and_b32_e32 v243, 0xffff0000, v150
	v_fmac_f32_e32 v244, v242, v242
	v_fmac_f32_e32 v245, v243, v243
	v_lshlrev_b32_e32 v242, 16, v151
	v_and_b32_e32 v243, 0xffff0000, v151
	v_fmac_f32_e32 v245, v242, v242
	v_fmac_f32_e32 v244, v243, v243
	s_waitcnt vmcnt(1)
	v_lshlrev_b32_e32 v242, 16, v152
	v_and_b32_e32 v243, 0xffff0000, v152
	v_fmac_f32_e32 v244, v242, v242
	v_fmac_f32_e32 v245, v243, v243
	v_lshlrev_b32_e32 v242, 16, v153
	v_and_b32_e32 v243, 0xffff0000, v153
	v_fmac_f32_e32 v245, v242, v242
	v_fmac_f32_e32 v244, v243, v243
	v_lshlrev_b32_e32 v242, 16, v154
	v_and_b32_e32 v243, 0xffff0000, v154
	v_fmac_f32_e32 v244, v242, v242
	v_fmac_f32_e32 v245, v243, v243
	v_lshlrev_b32_e32 v242, 16, v155
	v_and_b32_e32 v243, 0xffff0000, v155
	v_fmac_f32_e32 v245, v242, v242
	v_fmac_f32_e32 v244, v243, v243
	s_waitcnt vmcnt(0)
	v_lshlrev_b32_e32 v242, 16, v156
	v_and_b32_e32 v243, 0xffff0000, v156
	v_fmac_f32_e32 v244, v242, v242
	v_fmac_f32_e32 v245, v243, v243
	v_lshlrev_b32_e32 v242, 16, v157
	v_and_b32_e32 v243, 0xffff0000, v157
	v_fmac_f32_e32 v245, v242, v242
	v_fmac_f32_e32 v244, v243, v243
	v_lshlrev_b32_e32 v242, 16, v158
	v_and_b32_e32 v243, 0xffff0000, v158
	v_fmac_f32_e32 v244, v242, v242
	v_fmac_f32_e32 v245, v243, v243
	v_lshlrev_b32_e32 v242, 16, v159
	v_and_b32_e32 v243, 0xffff0000, v159
	v_fmac_f32_e32 v245, v242, v242
	v_fmac_f32_e32 v244, v243, v243
.Lqk_rs_done:
	v_add_f32_e32 v244, v244, v245
	s_nop 1
	v_add_f32_dpp v244, v244, v244 quad_perm:[1,0,3,2] row_mask:0xf bank_mask:0xf
	s_cmp_eq_u32 s60, 1
	s_mov_b32 s34, 0x3b800000
	s_cselect_b32 s34, 0x3b2aaaab, s34
	v_mov_b32_e32 v245, 0x358637bd
	v_fmac_f32_e32 v245, s34, v244
	v_rsq_f32_e32 v245, v245
	s_nop 0
	ds_write_b32 v239, v245
	s_waitcnt lgkmcnt(0)
	s_barrier
	ds_read_b32 v170, v237
	ds_read_b32 v171, v237 offset:128
	ds_read_b32 v172, v237 offset:256
	ds_read_b32 v173, v237 offset:384
	s_waitcnt lgkmcnt(0)
	s_cmp_eq_u32 s60, 1
	s_cbranch_scc0 .Lqk_epi_kv
	s_cmp_lt_u32 s62, 2
	s_cbranch_scc0 .Lqk_epi_qr
	s_mov_b32 s57, 0x3e16c740
	v_mul_f32_e32 v0, v0, v170
	v_mul_f32_e32 v0, s57, v0
	v_mul_f32_e32 v1, v1, v170
	v_mul_f32_e32 v1, s57, v1
	v_mul_f32_e32 v2, v2, v170
	v_mul_f32_e32 v2, s57, v2
	v_mul_f32_e32 v3, v3, v170
	v_mul_f32_e32 v3, s57, v3
	v_mul_f32_e32 v4, v4, v170
	v_mul_f32_e32 v4, s57, v4
	v_mul_f32_e32 v5, v5, v170
	v_mul_f32_e32 v5, s57, v5
	v_mul_f32_e32 v6, v6, v170
	v_mul_f32_e32 v6, s57, v6
	v_mul_f32_e32 v7, v7, v170
	v_mul_f32_e32 v7, s57, v7
	v_mul_f32_e32 v8, v8, v170
	v_mul_f32_e32 v8, s57, v8
	v_mul_f32_e32 v9, v9, v170
	v_mul_f32_e32 v9, s57, v9
	v_mul_f32_e32 v10, v10, v170
	v_mul_f32_e32 v10, s57, v10
	v_mul_f32_e32 v11, v11, v170
	v_mul_f32_e32 v11, s57, v11
	v_mul_f32_e32 v12, v12, v170
	v_mul_f32_e32 v12, s57, v12
	v_mul_f32_e32 v13, v13, v170
	v_mul_f32_e32 v13, s57, v13
	v_mul_f32_e32 v14, v14, v170
	v_mul_f32_e32 v14, s57, v14
	v_mul_f32_e32 v15, v15, v170
	v_mul_f32_e32 v15, s57, v15
	v_mul_f32_e32 v16, v16, v170
	v_mul_f32_e32 v16, s57, v16
	v_mul_f32_e32 v17, v17, v170
	v_mul_f32_e32 v17, s57, v17
	v_mul_f32_e32 v18, v18, v170
	v_mul_f32_e32 v18, s57, v18
	v_mul_f32_e32 v19, v19, v170
	v_mul_f32_e32 v19, s57, v19
	v_mul_f32_e32 v20, v20, v170
	v_mul_f32_e32 v20, s57, v20
	v_mul_f32_e32 v21, v21, v170
	v_mul_f32_e32 v21, s57, v21
	v_mul_f32_e32 v22, v22, v170
	v_mul_f32_e32 v22, s57, v22
	v_mul_f32_e32 v23, v23, v170
	v_mul_f32_e32 v23, s57, v23
	v_mul_f32_e32 v24, v24, v170
	v_mul_f32_e32 v24, s57, v24
	v_mul_f32_e32 v25, v25, v170
	v_mul_f32_e32 v25, s57, v25
	v_mul_f32_e32 v26, v26, v170
	v_mul_f32_e32 v26, s57, v26
	v_mul_f32_e32 v27, v27, v170
	v_mul_f32_e32 v27, s57, v27
	v_mul_f32_e32 v28, v28, v170
	v_mul_f32_e32 v28, s57, v28
	v_mul_f32_e32 v29, v29, v170
	v_mul_f32_e32 v29, s57, v29
	v_mul_f32_e32 v30, v30, v170
	v_mul_f32_e32 v30, s57, v30
	v_mul_f32_e32 v31, v31, v170
	v_mul_f32_e32 v31, s57, v31
	v_mul_f32_e32 v32, v32, v171
	v_mul_f32_e32 v32, s57, v32
	v_mul_f32_e32 v33, v33, v171
	v_mul_f32_e32 v33, s57, v33
	v_mul_f32_e32 v34, v34, v171
	v_mul_f32_e32 v34, s57, v34
	v_mul_f32_e32 v35, v35, v171
	v_mul_f32_e32 v35, s57, v35
	v_mul_f32_e32 v36, v36, v171
	v_mul_f32_e32 v36, s57, v36
	v_mul_f32_e32 v37, v37, v171
	v_mul_f32_e32 v37, s57, v37
	v_mul_f32_e32 v38, v38, v171
	v_mul_f32_e32 v38, s57, v38
	v_mul_f32_e32 v39, v39, v171
	v_mul_f32_e32 v39, s57, v39
	v_mul_f32_e32 v40, v40, v171
	v_mul_f32_e32 v40, s57, v40
	v_mul_f32_e32 v41, v41, v171
	v_mul_f32_e32 v41, s57, v41
	v_mul_f32_e32 v42, v42, v171
	v_mul_f32_e32 v42, s57, v42
	v_mul_f32_e32 v43, v43, v171
	v_mul_f32_e32 v43, s57, v43
	v_mul_f32_e32 v44, v44, v171
	v_mul_f32_e32 v44, s57, v44
	v_mul_f32_e32 v45, v45, v171
	v_mul_f32_e32 v45, s57, v45
	v_mul_f32_e32 v46, v46, v171
	v_mul_f32_e32 v46, s57, v46
	v_mul_f32_e32 v47, v47, v171
	v_mul_f32_e32 v47, s57, v47
	v_mul_f32_e32 v48, v48, v171
	v_mul_f32_e32 v48, s57, v48
	v_mul_f32_e32 v49, v49, v171
	v_mul_f32_e32 v49, s57, v49
	v_mul_f32_e32 v50, v50, v171
	v_mul_f32_e32 v50, s57, v50
	v_mul_f32_e32 v51, v51, v171
	v_mul_f32_e32 v51, s57, v51
	v_mul_f32_e32 v52, v52, v171
	v_mul_f32_e32 v52, s57, v52
	v_mul_f32_e32 v53, v53, v171
	v_mul_f32_e32 v53, s57, v53
	v_mul_f32_e32 v54, v54, v171
	v_mul_f32_e32 v54, s57, v54
	v_mul_f32_e32 v55, v55, v171
	v_mul_f32_e32 v55, s57, v55
	v_mul_f32_e32 v56, v56, v171
; DI int crow(int r, int hf) { return (r & 3) + 8 * (r >> 2) + 4 * hf; }
; DI void qkv_phase(const Params& p, int j, char* smem) {
;     ...
;               const int rr = rl + crow(r, hf_), t = m0_ + rr;
;               const float x = acc[i][jn][r] * rsc[moff + rr] * MLA_QSCALE;
;               if (C64 < 512) {
;                 Qb[(size_t)t * 768 + (C64 >> 6) * 96 + jn * 32 + l32_] = f2bf(x);
	v_mul_f32_e32 v56, s57, v56
	v_mul_f32_e32 v57, v57, v171
	v_mul_f32_e32 v57, s57, v57
	v_mul_f32_e32 v58, v58, v171
	v_mul_f32_e32 v58, s57, v58
	v_mul_f32_e32 v59, v59, v171
	v_mul_f32_e32 v59, s57, v59
	v_mul_f32_e32 v60, v60, v171
	v_mul_f32_e32 v60, s57, v60
	v_mul_f32_e32 v61, v61, v171
	v_mul_f32_e32 v61, s57, v61
	v_mul_f32_e32 v62, v62, v171
	v_mul_f32_e32 v62, s57, v62
	v_mul_f32_e32 v63, v63, v171
	v_mul_f32_e32 v63, s57, v63
	v_mul_f32_e32 v64, v64, v172
	v_mul_f32_e32 v64, s57, v64
	v_mul_f32_e32 v65, v65, v172
	v_mul_f32_e32 v65, s57, v65
	v_mul_f32_e32 v66, v66, v172
	v_mul_f32_e32 v66, s57, v66
	v_mul_f32_e32 v67, v67, v172
	v_mul_f32_e32 v67, s57, v67
	v_mul_f32_e32 v68, v68, v172
	v_mul_f32_e32 v68, s57, v68
	v_mul_f32_e32 v69, v69, v172
	v_mul_f32_e32 v69, s57, v69
	v_mul_f32_e32 v70, v70, v172
	v_mul_f32_e32 v70, s57, v70
	v_mul_f32_e32 v71, v71, v172
	v_mul_f32_e32 v71, s57, v71
	v_mul_f32_e32 v72, v72, v172
	v_mul_f32_e32 v72, s57, v72
	v_mul_f32_e32 v73, v73, v172
	v_mul_f32_e32 v73, s57, v73
	v_mul_f32_e32 v74, v74, v172
	v_mul_f32_e32 v74, s57, v74
	v_mul_f32_e32 v75, v75, v172
	v_mul_f32_e32 v75, s57, v75
	v_mul_f32_e32 v76, v76, v172
	v_mul_f32_e32 v76, s57, v76
	v_mul_f32_e32 v77, v77, v172
	v_mul_f32_e32 v77, s57, v77
	v_mul_f32_e32 v78, v78, v172
	v_mul_f32_e32 v78, s57, v78
	v_mul_f32_e32 v79, v79, v172
	v_mul_f32_e32 v79, s57, v79
	v_mul_f32_e32 v80, v80, v172
	v_mul_f32_e32 v80, s57, v80
	v_mul_f32_e32 v81, v81, v172
	v_mul_f32_e32 v81, s57, v81
	v_mul_f32_e32 v82, v82, v172
	v_mul_f32_e32 v82, s57, v82
	v_mul_f32_e32 v83, v83, v172
	v_mul_f32_e32 v83, s57, v83
	v_mul_f32_e32 v84, v84, v172
	v_mul_f32_e32 v84, s57, v84
	v_mul_f32_e32 v85, v85, v172
	v_mul_f32_e32 v85, s57, v85
	v_mul_f32_e32 v86, v86, v172
	v_mul_f32_e32 v86, s57, v86
	v_mul_f32_e32 v87, v87, v172
	v_mul_f32_e32 v87, s57, v87
	v_mul_f32_e32 v88, v88, v172
	v_mul_f32_e32 v88, s57, v88
	v_mul_f32_e32 v89, v89, v172
	v_mul_f32_e32 v89, s57, v89
	v_mul_f32_e32 v90, v90, v172
	v_mul_f32_e32 v90, s57, v90
	v_mul_f32_e32 v91, v91, v172
	v_mul_f32_e32 v91, s57, v91
	v_mul_f32_e32 v92, v92, v172
	v_mul_f32_e32 v92, s57, v92
	v_mul_f32_e32 v93, v93, v172
	v_mul_f32_e32 v93, s57, v93
	v_mul_f32_e32 v94, v94, v172
	v_mul_f32_e32 v94, s57, v94
	v_mul_f32_e32 v95, v95, v172
	v_mul_f32_e32 v95, s57, v95
	v_mul_f32_e32 v96, v96, v173
	v_mul_f32_e32 v96, s57, v96
	v_mul_f32_e32 v97, v97, v173
	v_mul_f32_e32 v97, s57, v97
	v_mul_f32_e32 v98, v98, v173
	v_mul_f32_e32 v98, s57, v98
	v_mul_f32_e32 v99, v99, v173
	v_mul_f32_e32 v99, s57, v99
	v_mul_f32_e32 v100, v100, v173
	v_mul_f32_e32 v100, s57, v100
	v_mul_f32_e32 v101, v101, v173
	v_mul_f32_e32 v101, s57, v101
	v_mul_f32_e32 v102, v102, v173
	v_mul_f32_e32 v102, s57, v102
	v_mul_f32_e32 v103, v103, v173
	v_mul_f32_e32 v103, s57, v103
	v_mul_f32_e32 v104, v104, v173
	v_mul_f32_e32 v104, s57, v104
	v_mul_f32_e32 v105, v105, v173
	v_mul_f32_e32 v105, s57, v105
	v_mul_f32_e32 v106, v106, v173
	v_mul_f32_e32 v106, s57, v106
	v_mul_f32_e32 v107, v107, v173
	v_mul_f32_e32 v107, s57, v107
	v_mul_f32_e32 v108, v108, v173
	v_mul_f32_e32 v108, s57, v108
	v_mul_f32_e32 v109, v109, v173
	v_mul_f32_e32 v109, s57, v109
	v_mul_f32_e32 v110, v110, v173
	v_mul_f32_e32 v110, s57, v110
	v_mul_f32_e32 v111, v111, v173
	v_mul_f32_e32 v111, s57, v111
	v_mul_f32_e32 v112, v112, v173
	v_mul_f32_e32 v112, s57, v112
	v_mul_f32_e32 v113, v113, v173
	v_mul_f32_e32 v113, s57, v113
	v_mul_f32_e32 v114, v114, v173
	v_mul_f32_e32 v114, s57, v114
	v_mul_f32_e32 v115, v115, v173
	v_mul_f32_e32 v115, s57, v115
	v_mul_f32_e32 v116, v116, v173
	v_mul_f32_e32 v116, s57, v116
	v_mul_f32_e32 v117, v117, v173
	v_mul_f32_e32 v117, s57, v117
	v_mul_f32_e32 v118, v118, v173
	v_mul_f32_e32 v118, s57, v118
	v_mul_f32_e32 v119, v119, v173
	v_mul_f32_e32 v119, s57, v119
	v_mul_f32_e32 v120, v120, v173
	v_mul_f32_e32 v120, s57, v120
	v_mul_f32_e32 v121, v121, v173
	v_mul_f32_e32 v121, s57, v121
	v_mul_f32_e32 v122, v122, v173
	v_mul_f32_e32 v122, s57, v122
	v_mul_f32_e32 v123, v123, v173
	v_mul_f32_e32 v123, s57, v123
	v_mul_f32_e32 v124, v124, v173
	v_mul_f32_e32 v124, s57, v124
	v_mul_f32_e32 v125, v125, v173
	v_mul_f32_e32 v125, s57, v125
	v_mul_f32_e32 v126, v126, v173
	v_mul_f32_e32 v126, s57, v126
	v_mul_f32_e32 v127, v127, v173
	v_mul_f32_e32 v127, s57, v127
	s_lshl_b32 s35, s62, 2
	s_add_u32 s35, s35, s13
	s_mul_i32 s35, s35, 0xc0
	s_mul_i32 s34, s56, 0x600
	s_add_u32 s34, s34, s35
	s_add_u32 s38, s0, s34
	s_addc_u32 s39, s1, 0
	s_add_u32 s38, s38, 0xf804100
	s_addc_u32 s39, s39, 0
	v_cvt_pk_bf16_f32 v240, v0, v1
	v_cvt_pk_bf16_f32 v241, v2, v3
	ds_write_b64 v178, v[240:241]
	v_cvt_pk_bf16_f32 v242, v4, v5
	v_cvt_pk_bf16_f32 v243, v6, v7
	ds_write_b64 v179, v[242:243]
	v_cvt_pk_bf16_f32 v244, v8, v9
	v_cvt_pk_bf16_f32 v245, v10, v11
	ds_write_b64 v180, v[244:245]
	v_cvt_pk_bf16_f32 v240, v12, v13
	v_cvt_pk_bf16_f32 v241, v14, v15
	ds_write_b64 v181, v[240:241]
	v_cvt_pk_bf16_f32 v242, v16, v17
	v_cvt_pk_bf16_f32 v243, v18, v19
	ds_write_b64 v188, v[242:243]
	v_cvt_pk_bf16_f32 v244, v20, v21
	v_cvt_pk_bf16_f32 v245, v22, v23
	ds_write_b64 v189, v[244:245]
	v_cvt_pk_bf16_f32 v240, v24, v25
	v_cvt_pk_bf16_f32 v241, v26, v27
	ds_write_b64 v190, v[240:241]
	v_cvt_pk_bf16_f32 v242, v28, v29
	v_cvt_pk_bf16_f32 v243, v30, v31
	ds_write_b64 v191, v[242:243]
	ds_read_b128 v[0:3], v194
	ds_read_b128 v[4:7], v194 offset:1024
	ds_read_b128 v[8:11], v194 offset:2048
	ds_read_b128 v[12:15], v194 offset:3072
	v_cvt_pk_bf16_f32 v244, v32, v33
	v_cvt_pk_bf16_f32 v245, v34, v35
	ds_write_b64 v178, v[244:245]
	v_cvt_pk_bf16_f32 v240, v36, v37
	v_cvt_pk_bf16_f32 v241, v38, v39
	ds_write_b64 v179, v[240:241]
	v_cvt_pk_bf16_f32 v242, v40, v41
	v_cvt_pk_bf16_f32 v243, v42, v43
	ds_write_b64 v180, v[242:243]
	v_cvt_pk_bf16_f32 v244, v44, v45
	v_cvt_pk_bf16_f32 v245, v46, v47
	ds_write_b64 v181, v[244:245]
	v_cvt_pk_bf16_f32 v240, v48, v49
	v_cvt_pk_bf16_f32 v241, v50, v51
	ds_write_b64 v188, v[240:241]
	v_cvt_pk_bf16_f32 v242, v52, v53
	v_cvt_pk_bf16_f32 v243, v54, v55
	ds_write_b64 v189, v[242:243]
	v_cvt_pk_bf16_f32 v244, v56, v57
	v_cvt_pk_bf16_f32 v245, v58, v59
	ds_write_b64 v190, v[244:245]
	v_cvt_pk_bf16_f32 v240, v60, v61
	v_cvt_pk_bf16_f32 v241, v62, v63
	ds_write_b64 v191, v[240:241]
	ds_read_b128 v[32:35], v194
	ds_read_b128 v[36:39], v194 offset:1024
	ds_read_b128 v[40:43], v194 offset:2048
	ds_read_b128 v[44:47], v194 offset:3072
	s_waitcnt lgkmcnt(12)
; DI int crow(int r, int hf) { return (r & 3) + 8 * (r >> 2) + 4 * hf; }
; DI void qkv_phase(const Params& p, int j, char* smem) {
;     ...
;               const int rr = rl + crow(r, hf_), t = m0_ + rr;
;               const float x = acc[i][jn][r] * rsc[moff + rr] * MLA_QSCALE;
;               if (C64 < 512) {
;                 Qb[(size_t)t * 768 + (C64 >> 6) * 96 + jn * 32 + l32_] = f2bf(x);
;               } else {
;                 const int hq = ((C64 - 512) >> 5) + jn, pos = t & (S_ - 1);
;                 const float xp = __shfl_xor(x, 16);
;                 const float2 cs = rt32[pos * 16 + (l32_ & 15)];
;                 const float o = (l32_ < 16) ? (x * cs.x - xp * cs.y) : (x * cs.x + xp * cs.y);
;                 Qb[(size_t)t * 768 + hq * 96 + 64 + l32_] = f2bf(o);
	global_store_dwordx4 v195, v[0:3], s[38:39] nt
	s_add_u32 s38, s38, 0x3000
	s_addc_u32 s39, s39, 0
	global_store_dwordx4 v195, v[4:7], s[38:39] nt
	s_add_u32 s38, s38, 0x3000
	s_addc_u32 s39, s39, 0
	global_store_dwordx4 v195, v[8:11], s[38:39] nt
	s_add_u32 s38, s38, 0x3000
	s_addc_u32 s39, s39, 0
	global_store_dwordx4 v195, v[12:15], s[38:39] nt
	s_add_u32 s38, s38, 0x3000
	s_addc_u32 s39, s39, 0
	v_cvt_pk_bf16_f32 v242, v64, v65
	v_cvt_pk_bf16_f32 v243, v66, v67
	ds_write_b64 v178, v[242:243]
	v_cvt_pk_bf16_f32 v244, v68, v69
	v_cvt_pk_bf16_f32 v245, v70, v71
	ds_write_b64 v179, v[244:245]
	v_cvt_pk_bf16_f32 v240, v72, v73
	v_cvt_pk_bf16_f32 v241, v74, v75
	ds_write_b64 v180, v[240:241]
	v_cvt_pk_bf16_f32 v242, v76, v77
	v_cvt_pk_bf16_f32 v243, v78, v79
	ds_write_b64 v181, v[242:243]
	v_cvt_pk_bf16_f32 v244, v80, v81
	v_cvt_pk_bf16_f32 v245, v82, v83
	ds_write_b64 v188, v[244:245]
	v_cvt_pk_bf16_f32 v240, v84, v85
	v_cvt_pk_bf16_f32 v241, v86, v87
	ds_write_b64 v189, v[240:241]
	v_cvt_pk_bf16_f32 v242, v88, v89
	v_cvt_pk_bf16_f32 v243, v90, v91
	ds_write_b64 v190, v[242:243]
	v_cvt_pk_bf16_f32 v244, v92, v93
	v_cvt_pk_bf16_f32 v245, v94, v95
	ds_write_b64 v191, v[244:245]
	ds_read_b128 v[64:67], v194
	ds_read_b128 v[68:71], v194 offset:1024
	ds_read_b128 v[72:75], v194 offset:2048
	ds_read_b128 v[76:79], v194 offset:3072
	s_waitcnt lgkmcnt(12)
	global_store_dwordx4 v195, v[32:35], s[38:39] nt
	s_add_u32 s38, s38, 0x3000
	s_addc_u32 s39, s39, 0
	global_store_dwordx4 v195, v[36:39], s[38:39] nt
	s_add_u32 s38, s38, 0x3000
	s_addc_u32 s39, s39, 0
	global_store_dwordx4 v195, v[40:43], s[38:39] nt
	s_add_u32 s38, s38, 0x3000
	s_addc_u32 s39, s39, 0
	global_store_dwordx4 v195, v[44:47], s[38:39] nt
	s_add_u32 s38, s38, 0x3000
	s_addc_u32 s39, s39, 0
	v_cvt_pk_bf16_f32 v240, v96, v97
	v_cvt_pk_bf16_f32 v241, v98, v99
	ds_write_b64 v178, v[240:241]
	v_cvt_pk_bf16_f32 v242, v100, v101
	v_cvt_pk_bf16_f32 v243, v102, v103
	ds_write_b64 v179, v[242:243]
	v_cvt_pk_bf16_f32 v244, v104, v105
	v_cvt_pk_bf16_f32 v245, v106, v107
	ds_write_b64 v180, v[244:245]
	v_cvt_pk_bf16_f32 v240, v108, v109
	v_cvt_pk_bf16_f32 v241, v110, v111
	ds_write_b64 v181, v[240:241]
	v_cvt_pk_bf16_f32 v242, v112, v113
	v_cvt_pk_bf16_f32 v243, v114, v115
	ds_write_b64 v188, v[242:243]
	v_cvt_pk_bf16_f32 v244, v116, v117
	v_cvt_pk_bf16_f32 v245, v118, v119
	ds_write_b64 v189, v[244:245]
	v_cvt_pk_bf16_f32 v240, v120, v121
	v_cvt_pk_bf16_f32 v241, v122, v123
	ds_write_b64 v190, v[240:241]
	v_cvt_pk_bf16_f32 v242, v124, v125
	v_cvt_pk_bf16_f32 v243, v126, v127
	ds_write_b64 v191, v[242:243]
	ds_read_b128 v[96:99], v194
	ds_read_b128 v[100:103], v194 offset:1024
	ds_read_b128 v[104:107], v194 offset:2048
	ds_read_b128 v[108:111], v194 offset:3072
	s_waitcnt lgkmcnt(12)
	global_store_dwordx4 v195, v[64:67], s[38:39] nt
	s_add_u32 s38, s38, 0x3000
	s_addc_u32 s39, s39, 0
	global_store_dwordx4 v195, v[68:71], s[38:39] nt
	s_add_u32 s38, s38, 0x3000
	s_addc_u32 s39, s39, 0
	global_store_dwordx4 v195, v[72:75], s[38:39] nt
	s_add_u32 s38, s38, 0x3000
	s_addc_u32 s39, s39, 0
	global_store_dwordx4 v195, v[76:79], s[38:39] nt
	s_add_u32 s38, s38, 0x3000
	s_addc_u32 s39, s39, 0
	s_waitcnt lgkmcnt(0)
	global_store_dwordx4 v195, v[96:99], s[38:39] nt
	s_add_u32 s38, s38, 0x3000
	s_addc_u32 s39, s39, 0
	global_store_dwordx4 v195, v[100:103], s[38:39] nt
	s_add_u32 s38, s38, 0x3000
	s_addc_u32 s39, s39, 0
	global_store_dwordx4 v195, v[104:107], s[38:39] nt
	s_add_u32 s38, s38, 0x3000
	s_addc_u32 s39, s39, 0
	global_store_dwordx4 v195, v[108:111], s[38:39] nt
	s_branch .Lqk_epi_done
.Lqk_epi_qr:
	s_mov_b32 s57, 0x3e16c740
	v_mul_f32_e32 v0, v0, v170
	v_mul_f32_e32 v0, s57, v0
	v_mul_f32_e32 v1, v1, v170
	v_mul_f32_e32 v1, s57, v1
	v_mul_f32_e32 v2, v2, v170
	v_mul_f32_e32 v2, s57, v2
	v_mul_f32_e32 v3, v3, v170
	v_mul_f32_e32 v3, s57, v3
	v_mul_f32_e32 v4, v4, v170
	v_mul_f32_e32 v4, s57, v4
	v_mul_f32_e32 v5, v5, v170
	v_mul_f32_e32 v5, s57, v5
	v_mul_f32_e32 v6, v6, v170
	v_mul_f32_e32 v6, s57, v6
	v_mul_f32_e32 v7, v7, v170
	v_mul_f32_e32 v7, s57, v7
	v_mul_f32_e32 v8, v8, v170
	v_mul_f32_e32 v8, s57, v8
	v_mul_f32_e32 v9, v9, v170
	v_mul_f32_e32 v9, s57, v9
	v_mul_f32_e32 v10, v10, v170
	v_mul_f32_e32 v10, s57, v10
	v_mul_f32_e32 v11, v11, v170
	v_mul_f32_e32 v11, s57, v11
	v_mul_f32_e32 v12, v12, v170
	v_mul_f32_e32 v12, s57, v12
	v_mul_f32_e32 v13, v13, v170
	v_mul_f32_e32 v13, s57, v13
	v_mul_f32_e32 v14, v14, v170
	v_mul_f32_e32 v14, s57, v14
	v_mul_f32_e32 v15, v15, v170
	v_mul_f32_e32 v15, s57, v15
	v_mul_f32_e32 v16, v16, v170
	v_mul_f32_e32 v16, s57, v16
	v_mul_f32_e32 v17, v17, v170
	v_mul_f32_e32 v17, s57, v17
	v_mul_f32_e32 v18, v18, v170
	v_mul_f32_e32 v18, s57, v18
	v_mul_f32_e32 v19, v19, v170
	v_mul_f32_e32 v19, s57, v19
	v_mul_f32_e32 v20, v20, v170
	v_mul_f32_e32 v20, s57, v20
	v_mul_f32_e32 v21, v21, v170
	v_mul_f32_e32 v21, s57, v21
	v_mul_f32_e32 v22, v22, v170
	v_mul_f32_e32 v22, s57, v22
	v_mul_f32_e32 v23, v23, v170
	v_mul_f32_e32 v23, s57, v23
	v_mul_f32_e32 v24, v24, v170
	v_mul_f32_e32 v24, s57, v24
	v_mul_f32_e32 v25, v25, v170
	v_mul_f32_e32 v25, s57, v25
	v_mul_f32_e32 v26, v26, v170
	v_mul_f32_e32 v26, s57, v26
	v_mul_f32_e32 v27, v27, v170
	v_mul_f32_e32 v27, s57, v27
	v_mul_f32_e32 v28, v28, v170
	v_mul_f32_e32 v28, s57, v28
	v_mul_f32_e32 v29, v29, v170
	v_mul_f32_e32 v29, s57, v29
	v_mul_f32_e32 v30, v30, v170
	v_mul_f32_e32 v30, s57, v30
	v_mul_f32_e32 v31, v31, v170
	v_mul_f32_e32 v31, s57, v31
	v_mul_f32_e32 v32, v32, v171
	v_mul_f32_e32 v32, s57, v32
	v_mul_f32_e32 v33, v33, v171
	v_mul_f32_e32 v33, s57, v33
	v_mul_f32_e32 v34, v34, v171
; DI void qkv_phase(const Params& p, int j, char* smem) {
;     ...
;               const float x = acc[i][jn][r] * rsc[moff + rr] * MLA_QSCALE;
;               if (C64 < 512) {
;                 Qb[(size_t)t * 768 + (C64 >> 6) * 96 + jn * 32 + l32_] = f2bf(x);
;               } else {
;                 const int hq = ((C64 - 512) >> 5) + jn, pos = t & (S_ - 1);
;                 const float xp = __shfl_xor(x, 16);
;                 const float2 cs = rt32[pos * 16 + (l32_ & 15)];
;                 const float o = (l32_ < 16) ? (x * cs.x - xp * cs.y) : (x * cs.x + xp * cs.y);
	v_mul_f32_e32 v34, s57, v34
	v_mul_f32_e32 v35, v35, v171
	v_mul_f32_e32 v35, s57, v35
	v_mul_f32_e32 v36, v36, v171
	v_mul_f32_e32 v36, s57, v36
	v_mul_f32_e32 v37, v37, v171
	v_mul_f32_e32 v37, s57, v37
	v_mul_f32_e32 v38, v38, v171
	v_mul_f32_e32 v38, s57, v38
	v_mul_f32_e32 v39, v39, v171
	v_mul_f32_e32 v39, s57, v39
	v_mul_f32_e32 v40, v40, v171
	v_mul_f32_e32 v40, s57, v40
	v_mul_f32_e32 v41, v41, v171
	v_mul_f32_e32 v41, s57, v41
	v_mul_f32_e32 v42, v42, v171
	v_mul_f32_e32 v42, s57, v42
	v_mul_f32_e32 v43, v43, v171
	v_mul_f32_e32 v43, s57, v43
	v_mul_f32_e32 v44, v44, v171
	v_mul_f32_e32 v44, s57, v44
	v_mul_f32_e32 v45, v45, v171
	v_mul_f32_e32 v45, s57, v45
	v_mul_f32_e32 v46, v46, v171
	v_mul_f32_e32 v46, s57, v46
	v_mul_f32_e32 v47, v47, v171
	v_mul_f32_e32 v47, s57, v47
	v_mul_f32_e32 v48, v48, v171
	v_mul_f32_e32 v48, s57, v48
	v_mul_f32_e32 v49, v49, v171
	v_mul_f32_e32 v49, s57, v49
	v_mul_f32_e32 v50, v50, v171
	v_mul_f32_e32 v50, s57, v50
	v_mul_f32_e32 v51, v51, v171
	v_mul_f32_e32 v51, s57, v51
	v_mul_f32_e32 v52, v52, v171
	v_mul_f32_e32 v52, s57, v52
	v_mul_f32_e32 v53, v53, v171
	v_mul_f32_e32 v53, s57, v53
	v_mul_f32_e32 v54, v54, v171
	v_mul_f32_e32 v54, s57, v54
	v_mul_f32_e32 v55, v55, v171
	v_mul_f32_e32 v55, s57, v55
	v_mul_f32_e32 v56, v56, v171
	v_mul_f32_e32 v56, s57, v56
	v_mul_f32_e32 v57, v57, v171
	v_mul_f32_e32 v57, s57, v57
	v_mul_f32_e32 v58, v58, v171
	v_mul_f32_e32 v58, s57, v58
	v_mul_f32_e32 v59, v59, v171
	v_mul_f32_e32 v59, s57, v59
	v_mul_f32_e32 v60, v60, v171
	v_mul_f32_e32 v60, s57, v60
	v_mul_f32_e32 v61, v61, v171
	v_mul_f32_e32 v61, s57, v61
	v_mul_f32_e32 v62, v62, v171
	v_mul_f32_e32 v62, s57, v62
	v_mul_f32_e32 v63, v63, v171
	v_mul_f32_e32 v63, s57, v63
	v_mul_f32_e32 v64, v64, v172
	v_mul_f32_e32 v64, s57, v64
	v_mul_f32_e32 v65, v65, v172
	v_mul_f32_e32 v65, s57, v65
	v_mul_f32_e32 v66, v66, v172
	v_mul_f32_e32 v66, s57, v66
	v_mul_f32_e32 v67, v67, v172
	v_mul_f32_e32 v67, s57, v67
	v_mul_f32_e32 v68, v68, v172
	v_mul_f32_e32 v68, s57, v68
	v_mul_f32_e32 v69, v69, v172
	v_mul_f32_e32 v69, s57, v69
	v_mul_f32_e32 v70, v70, v172
	v_mul_f32_e32 v70, s57, v70
	v_mul_f32_e32 v71, v71, v172
	v_mul_f32_e32 v71, s57, v71
	v_mul_f32_e32 v72, v72, v172
	v_mul_f32_e32 v72, s57, v72
	v_mul_f32_e32 v73, v73, v172
	v_mul_f32_e32 v73, s57, v73
	v_mul_f32_e32 v74, v74, v172
	v_mul_f32_e32 v74, s57, v74
	v_mul_f32_e32 v75, v75, v172
	v_mul_f32_e32 v75, s57, v75
	v_mul_f32_e32 v76, v76, v172
	v_mul_f32_e32 v76, s57, v76
	v_mul_f32_e32 v77, v77, v172
	v_mul_f32_e32 v77, s57, v77
	v_mul_f32_e32 v78, v78, v172
	v_mul_f32_e32 v78, s57, v78
	v_mul_f32_e32 v79, v79, v172
	v_mul_f32_e32 v79, s57, v79
	v_mul_f32_e32 v80, v80, v172
	v_mul_f32_e32 v80, s57, v80
	v_mul_f32_e32 v81, v81, v172
	v_mul_f32_e32 v81, s57, v81
	v_mul_f32_e32 v82, v82, v172
	v_mul_f32_e32 v82, s57, v82
	v_mul_f32_e32 v83, v83, v172
	v_mul_f32_e32 v83, s57, v83
	v_mul_f32_e32 v84, v84, v172
	v_mul_f32_e32 v84, s57, v84
	v_mul_f32_e32 v85, v85, v172
	v_mul_f32_e32 v85, s57, v85
	v_mul_f32_e32 v86, v86, v172
	v_mul_f32_e32 v86, s57, v86
	v_mul_f32_e32 v87, v87, v172
	v_mul_f32_e32 v87, s57, v87
	v_mul_f32_e32 v88, v88, v172
	v_mul_f32_e32 v88, s57, v88
	v_mul_f32_e32 v89, v89, v172
	v_mul_f32_e32 v89, s57, v89
	v_mul_f32_e32 v90, v90, v172
	v_mul_f32_e32 v90, s57, v90
	v_mul_f32_e32 v91, v91, v172
	v_mul_f32_e32 v91, s57, v91
	v_mul_f32_e32 v92, v92, v172
	v_mul_f32_e32 v92, s57, v92
	v_mul_f32_e32 v93, v93, v172
	v_mul_f32_e32 v93, s57, v93
	v_mul_f32_e32 v94, v94, v172
	v_mul_f32_e32 v94, s57, v94
	v_mul_f32_e32 v95, v95, v172
	v_mul_f32_e32 v95, s57, v95
	v_mul_f32_e32 v96, v96, v173
	v_mul_f32_e32 v96, s57, v96
	v_mul_f32_e32 v97, v97, v173
	v_mul_f32_e32 v97, s57, v97
	v_mul_f32_e32 v98, v98, v173
	v_mul_f32_e32 v98, s57, v98
	v_mul_f32_e32 v99, v99, v173
	v_mul_f32_e32 v99, s57, v99
	v_mul_f32_e32 v100, v100, v173
	v_mul_f32_e32 v100, s57, v100
	v_mul_f32_e32 v101, v101, v173
	v_mul_f32_e32 v101, s57, v101
	v_mul_f32_e32 v102, v102, v173
	v_mul_f32_e32 v102, s57, v102
	v_mul_f32_e32 v103, v103, v173
	v_mul_f32_e32 v103, s57, v103
	v_mul_f32_e32 v104, v104, v173
	v_mul_f32_e32 v104, s57, v104
	v_mul_f32_e32 v105, v105, v173
	v_mul_f32_e32 v105, s57, v105
	v_mul_f32_e32 v106, v106, v173
	v_mul_f32_e32 v106, s57, v106
	v_mul_f32_e32 v107, v107, v173
	v_mul_f32_e32 v107, s57, v107
	v_mul_f32_e32 v108, v108, v173
	v_mul_f32_e32 v108, s57, v108
	v_mul_f32_e32 v109, v109, v173
	v_mul_f32_e32 v109, s57, v109
	v_mul_f32_e32 v110, v110, v173
	v_mul_f32_e32 v110, s57, v110
	v_mul_f32_e32 v111, v111, v173
	v_mul_f32_e32 v111, s57, v111
	v_mul_f32_e32 v112, v112, v173
	v_mul_f32_e32 v112, s57, v112
	v_mul_f32_e32 v113, v113, v173
	v_mul_f32_e32 v113, s57, v113
	v_mul_f32_e32 v114, v114, v173
	v_mul_f32_e32 v114, s57, v114
	v_mul_f32_e32 v115, v115, v173
	v_mul_f32_e32 v115, s57, v115
	v_mul_f32_e32 v116, v116, v173
	v_mul_f32_e32 v116, s57, v116
	v_mul_f32_e32 v117, v117, v173
	v_mul_f32_e32 v117, s57, v117
	v_mul_f32_e32 v118, v118, v173
	v_mul_f32_e32 v118, s57, v118
	v_mul_f32_e32 v119, v119, v173
	v_mul_f32_e32 v119, s57, v119
	v_mul_f32_e32 v120, v120, v173
	v_mul_f32_e32 v120, s57, v120
	v_mul_f32_e32 v121, v121, v173
	v_mul_f32_e32 v121, s57, v121
	v_mul_f32_e32 v122, v122, v173
	v_mul_f32_e32 v122, s57, v122
	v_mul_f32_e32 v123, v123, v173
	v_mul_f32_e32 v123, s57, v123
	v_mul_f32_e32 v124, v124, v173
	v_mul_f32_e32 v124, s57, v124
	v_mul_f32_e32 v125, v125, v173
	v_mul_f32_e32 v125, s57, v125
	v_mul_f32_e32 v126, v126, v173
	v_mul_f32_e32 v126, s57, v126
	v_mul_f32_e32 v127, v127, v173
	v_mul_f32_e32 v127, s57, v127
	s_and_b32 s34, s56, 0x3fff
	s_lshl_b32 s34, s34, 7
	s_add_u32 s40, s0, s34
	s_addc_u32 s41, s1, 0
	s_add_u32 s40, s40, 0x34100
	s_addc_u32 s41, s41, 0
	s_add_u32 s34, s40, 0x0
	s_addc_u32 s35, s41, 0
	global_load_dwordx4 v[128:131], v160, s[34:35]
	global_load_dwordx4 v[132:135], v160, s[34:35] offset:16
	global_load_dwordx4 v[136:139], v160, s[34:35] offset:64
	global_load_dwordx4 v[140:143], v160, s[34:35] offset:80
	s_add_u32 s34, s40, 0x1000
	s_addc_u32 s35, s41, 0
	global_load_dwordx4 v[144:147], v160, s[34:35]
	global_load_dwordx4 v[148:151], v160, s[34:35] offset:16
	global_load_dwordx4 v[152:155], v160, s[34:35] offset:64
	global_load_dwordx4 v[156:159], v160, s[34:35] offset:80
	s_waitcnt vmcnt(4)
; DI void qkv_phase(const Params& p, int j, char* smem) {
;     ...
;                 const int hq = ((C64 - 512) >> 5) + jn, pos = t & (S_ - 1);
;                 const float xp = __shfl_xor(x, 16);
;                 const float2 cs = rt32[pos * 16 + (l32_ & 15)];
;                 const float o = (l32_ < 16) ? (x * cs.x - xp * cs.y) : (x * cs.x + xp * cs.y);
;                 Qb[(size_t)t * 768 + hq * 96 + 64 + l32_] = f2bf(o);
	v_mul_f32_e32 v246, v8, v129
	v_mul_f32_e32 v247, v0, v129
	v_fma_f32 v0, v0, v128, -v246
	v_fma_f32 v8, v8, v128, v247
	v_mul_f32_e32 v246, v9, v131
	v_mul_f32_e32 v247, v1, v131
	v_fma_f32 v1, v1, v130, -v246
	v_fma_f32 v9, v9, v130, v247
	v_mul_f32_e32 v246, v10, v133
	v_mul_f32_e32 v247, v2, v133
	v_fma_f32 v2, v2, v132, -v246
	v_fma_f32 v10, v10, v132, v247
	v_mul_f32_e32 v246, v11, v135
	v_mul_f32_e32 v247, v3, v135
	v_fma_f32 v3, v3, v134, -v246
	v_fma_f32 v11, v11, v134, v247
	v_mul_f32_e32 v246, v12, v137
	v_mul_f32_e32 v247, v4, v137
	v_fma_f32 v4, v4, v136, -v246
	v_fma_f32 v12, v12, v136, v247
	v_mul_f32_e32 v246, v13, v139
	v_mul_f32_e32 v247, v5, v139
	v_fma_f32 v5, v5, v138, -v246
	v_fma_f32 v13, v13, v138, v247
	v_mul_f32_e32 v246, v14, v141
	v_mul_f32_e32 v247, v6, v141
	v_fma_f32 v6, v6, v140, -v246
	v_fma_f32 v14, v14, v140, v247
	v_mul_f32_e32 v246, v15, v143
	v_mul_f32_e32 v247, v7, v143
	v_fma_f32 v7, v7, v142, -v246
	v_fma_f32 v15, v15, v142, v247
	v_mul_f32_e32 v246, v24, v129
	v_mul_f32_e32 v247, v16, v129
	v_fma_f32 v16, v16, v128, -v246
	v_fma_f32 v24, v24, v128, v247
	v_mul_f32_e32 v246, v25, v131
	v_mul_f32_e32 v247, v17, v131
	v_fma_f32 v17, v17, v130, -v246
	v_fma_f32 v25, v25, v130, v247
	v_mul_f32_e32 v246, v26, v133
	v_mul_f32_e32 v247, v18, v133
	v_fma_f32 v18, v18, v132, -v246
	v_fma_f32 v26, v26, v132, v247
	v_mul_f32_e32 v246, v27, v135
	v_mul_f32_e32 v247, v19, v135
	v_fma_f32 v19, v19, v134, -v246
	v_fma_f32 v27, v27, v134, v247
	v_mul_f32_e32 v246, v28, v137
	v_mul_f32_e32 v247, v20, v137
	v_fma_f32 v20, v20, v136, -v246
	v_fma_f32 v28, v28, v136, v247
	v_mul_f32_e32 v246, v29, v139
	v_mul_f32_e32 v247, v21, v139
	v_fma_f32 v21, v21, v138, -v246
	v_fma_f32 v29, v29, v138, v247
	v_mul_f32_e32 v246, v30, v141
	v_mul_f32_e32 v247, v22, v141
	v_fma_f32 v22, v22, v140, -v246
	v_fma_f32 v30, v30, v140, v247
	v_mul_f32_e32 v246, v31, v143
	v_mul_f32_e32 v247, v23, v143
	v_fma_f32 v23, v23, v142, -v246
	v_fma_f32 v31, v31, v142, v247
	s_add_u32 s34, s40, 0x2000
	s_addc_u32 s35, s41, 0
	global_load_dwordx4 v[128:131], v160, s[34:35]
	global_load_dwordx4 v[132:135], v160, s[34:35] offset:16
	global_load_dwordx4 v[136:139], v160, s[34:35] offset:64
	global_load_dwordx4 v[140:143], v160, s[34:35] offset:80
	s_waitcnt vmcnt(4)
	v_mul_f32_e32 v246, v40, v145
	v_mul_f32_e32 v247, v32, v145
	v_fma_f32 v32, v32, v144, -v246
	v_fma_f32 v40, v40, v144, v247
	v_mul_f32_e32 v246, v41, v147
	v_mul_f32_e32 v247, v33, v147
	v_fma_f32 v33, v33, v146, -v246
	v_fma_f32 v41, v41, v146, v247
	v_mul_f32_e32 v246, v42, v149
	v_mul_f32_e32 v247, v34, v149
	v_fma_f32 v34, v34, v148, -v246
	v_fma_f32 v42, v42, v148, v247
	v_mul_f32_e32 v246, v43, v151
	v_mul_f32_e32 v247, v35, v151
	v_fma_f32 v35, v35, v150, -v246
	v_fma_f32 v43, v43, v150, v247
	v_mul_f32_e32 v246, v44, v153
	v_mul_f32_e32 v247, v36, v153
	v_fma_f32 v36, v36, v152, -v246
	v_fma_f32 v44, v44, v152, v247
	v_mul_f32_e32 v246, v45, v155
	v_mul_f32_e32 v247, v37, v155
	v_fma_f32 v37, v37, v154, -v246
	v_fma_f32 v45, v45, v154, v247
	v_mul_f32_e32 v246, v46, v157
	v_mul_f32_e32 v247, v38, v157
	v_fma_f32 v38, v38, v156, -v246
	v_fma_f32 v46, v46, v156, v247
	v_mul_f32_e32 v246, v47, v159
	v_mul_f32_e32 v247, v39, v159
	v_fma_f32 v39, v39, v158, -v246
	v_fma_f32 v47, v47, v158, v247
	v_mul_f32_e32 v246, v56, v145
	v_mul_f32_e32 v247, v48, v145
	v_fma_f32 v48, v48, v144, -v246
	v_fma_f32 v56, v56, v144, v247
	v_mul_f32_e32 v246, v57, v147
	v_mul_f32_e32 v247, v49, v147
	v_fma_f32 v49, v49, v146, -v246
	v_fma_f32 v57, v57, v146, v247
	v_mul_f32_e32 v246, v58, v149
	v_mul_f32_e32 v247, v50, v149
	v_fma_f32 v50, v50, v148, -v246
	v_fma_f32 v58, v58, v148, v247
	v_mul_f32_e32 v246, v59, v151
	v_mul_f32_e32 v247, v51, v151
	v_fma_f32 v51, v51, v150, -v246
	v_fma_f32 v59, v59, v150, v247
	v_mul_f32_e32 v246, v60, v153
	v_mul_f32_e32 v247, v52, v153
	v_fma_f32 v52, v52, v152, -v246
	v_fma_f32 v60, v60, v152, v247
	v_mul_f32_e32 v246, v61, v155
	v_mul_f32_e32 v247, v53, v155
	v_fma_f32 v53, v53, v154, -v246
	v_fma_f32 v61, v61, v154, v247
	v_mul_f32_e32 v246, v62, v157
	v_mul_f32_e32 v247, v54, v157
	v_fma_f32 v54, v54, v156, -v246
	v_fma_f32 v62, v62, v156, v247
	v_mul_f32_e32 v246, v63, v159
	v_mul_f32_e32 v247, v55, v159
	v_fma_f32 v55, v55, v158, -v246
	v_fma_f32 v63, v63, v158, v247
	s_add_u32 s34, s40, 0x3000
	s_addc_u32 s35, s41, 0
	global_load_dwordx4 v[144:147], v160, s[34:35]
	global_load_dwordx4 v[148:151], v160, s[34:35] offset:16
	global_load_dwordx4 v[152:155], v160, s[34:35] offset:64
	global_load_dwordx4 v[156:159], v160, s[34:35] offset:80
	s_waitcnt vmcnt(4)
; DI void qkv_phase(const Params& p, int j, char* smem) {
;     ...
;                 const int hq = ((C64 - 512) >> 5) + jn, pos = t & (S_ - 1);
;                 const float xp = __shfl_xor(x, 16);
;                 const float2 cs = rt32[pos * 16 + (l32_ & 15)];
;                 const float o = (l32_ < 16) ? (x * cs.x - xp * cs.y) : (x * cs.x + xp * cs.y);
;                 Qb[(size_t)t * 768 + hq * 96 + 64 + l32_] = f2bf(o);
	v_mul_f32_e32 v246, v72, v129
	v_mul_f32_e32 v247, v64, v129
	v_fma_f32 v64, v64, v128, -v246
	v_fma_f32 v72, v72, v128, v247
	v_mul_f32_e32 v246, v73, v131
	v_mul_f32_e32 v247, v65, v131
	v_fma_f32 v65, v65, v130, -v246
	v_fma_f32 v73, v73, v130, v247
	v_mul_f32_e32 v246, v74, v133
	v_mul_f32_e32 v247, v66, v133
	v_fma_f32 v66, v66, v132, -v246
	v_fma_f32 v74, v74, v132, v247
	v_mul_f32_e32 v246, v75, v135
	v_mul_f32_e32 v247, v67, v135
	v_fma_f32 v67, v67, v134, -v246
	v_fma_f32 v75, v75, v134, v247
	v_mul_f32_e32 v246, v76, v137
	v_mul_f32_e32 v247, v68, v137
	v_fma_f32 v68, v68, v136, -v246
	v_fma_f32 v76, v76, v136, v247
	v_mul_f32_e32 v246, v77, v139
	v_mul_f32_e32 v247, v69, v139
	v_fma_f32 v69, v69, v138, -v246
	v_fma_f32 v77, v77, v138, v247
	v_mul_f32_e32 v246, v78, v141
	v_mul_f32_e32 v247, v70, v141
	v_fma_f32 v70, v70, v140, -v246
	v_fma_f32 v78, v78, v140, v247
	v_mul_f32_e32 v246, v79, v143
	v_mul_f32_e32 v247, v71, v143
	v_fma_f32 v71, v71, v142, -v246
	v_fma_f32 v79, v79, v142, v247
	v_mul_f32_e32 v246, v88, v129
	v_mul_f32_e32 v247, v80, v129
	v_fma_f32 v80, v80, v128, -v246
	v_fma_f32 v88, v88, v128, v247
	v_mul_f32_e32 v246, v89, v131
	v_mul_f32_e32 v247, v81, v131
	v_fma_f32 v81, v81, v130, -v246
	v_fma_f32 v89, v89, v130, v247
	v_mul_f32_e32 v246, v90, v133
	v_mul_f32_e32 v247, v82, v133
	v_fma_f32 v82, v82, v132, -v246
	v_fma_f32 v90, v90, v132, v247
	v_mul_f32_e32 v246, v91, v135
	v_mul_f32_e32 v247, v83, v135
	v_fma_f32 v83, v83, v134, -v246
	v_fma_f32 v91, v91, v134, v247
	v_mul_f32_e32 v246, v92, v137
	v_mul_f32_e32 v247, v84, v137
	v_fma_f32 v84, v84, v136, -v246
	v_fma_f32 v92, v92, v136, v247
	v_mul_f32_e32 v246, v93, v139
	v_mul_f32_e32 v247, v85, v139
	v_fma_f32 v85, v85, v138, -v246
	v_fma_f32 v93, v93, v138, v247
	v_mul_f32_e32 v246, v94, v141
	v_mul_f32_e32 v247, v86, v141
	v_fma_f32 v86, v86, v140, -v246
	v_fma_f32 v94, v94, v140, v247
	v_mul_f32_e32 v246, v95, v143
	v_mul_f32_e32 v247, v87, v143
	v_fma_f32 v87, v87, v142, -v246
	v_fma_f32 v95, v95, v142, v247
	s_waitcnt vmcnt(0)
	v_mul_f32_e32 v246, v104, v145
	v_mul_f32_e32 v247, v96, v145
	v_fma_f32 v96, v96, v144, -v246
	v_fma_f32 v104, v104, v144, v247
	v_mul_f32_e32 v246, v105, v147
	v_mul_f32_e32 v247, v97, v147
	v_fma_f32 v97, v97, v146, -v246
	v_fma_f32 v105, v105, v146, v247
	v_mul_f32_e32 v246, v106, v149
	v_mul_f32_e32 v247, v98, v149
	v_fma_f32 v98, v98, v148, -v246
	v_fma_f32 v106, v106, v148, v247
	v_mul_f32_e32 v246, v107, v151
	v_mul_f32_e32 v247, v99, v151
	v_fma_f32 v99, v99, v150, -v246
	v_fma_f32 v107, v107, v150, v247
	v_mul_f32_e32 v246, v108, v153
	v_mul_f32_e32 v247, v100, v153
	v_fma_f32 v100, v100, v152, -v246
	v_fma_f32 v108, v108, v152, v247
	v_mul_f32_e32 v246, v109, v155
	v_mul_f32_e32 v247, v101, v155
	v_fma_f32 v101, v101, v154, -v246
	v_fma_f32 v109, v109, v154, v247
	v_mul_f32_e32 v246, v110, v157
	v_mul_f32_e32 v247, v102, v157
	v_fma_f32 v102, v102, v156, -v246
	v_fma_f32 v110, v110, v156, v247
	v_mul_f32_e32 v246, v111, v159
	v_mul_f32_e32 v247, v103, v159
	v_fma_f32 v103, v103, v158, -v246
	v_fma_f32 v111, v111, v158, v247
	v_mul_f32_e32 v246, v120, v145
	v_mul_f32_e32 v247, v112, v145
	v_fma_f32 v112, v112, v144, -v246
	v_fma_f32 v120, v120, v144, v247
	v_mul_f32_e32 v246, v121, v147
	v_mul_f32_e32 v247, v113, v147
	v_fma_f32 v113, v113, v146, -v246
	v_fma_f32 v121, v121, v146, v247
	v_mul_f32_e32 v246, v122, v149
	v_mul_f32_e32 v247, v114, v149
	v_fma_f32 v114, v114, v148, -v246
	v_fma_f32 v122, v122, v148, v247
	v_mul_f32_e32 v246, v123, v151
	v_mul_f32_e32 v247, v115, v151
	v_fma_f32 v115, v115, v150, -v246
	v_fma_f32 v123, v123, v150, v247
	v_mul_f32_e32 v246, v124, v153
	v_mul_f32_e32 v247, v116, v153
	v_fma_f32 v116, v116, v152, -v246
	v_fma_f32 v124, v124, v152, v247
	v_mul_f32_e32 v246, v125, v155
	v_mul_f32_e32 v247, v117, v155
	v_fma_f32 v117, v117, v154, -v246
	v_fma_f32 v125, v125, v154, v247
	v_mul_f32_e32 v246, v126, v157
	v_mul_f32_e32 v247, v118, v157
	v_fma_f32 v118, v118, v156, -v246
	v_fma_f32 v126, v126, v156, v247
	v_mul_f32_e32 v246, v127, v159
	v_mul_f32_e32 v247, v119, v159
	v_fma_f32 v119, v119, v158, -v246
	v_fma_f32 v127, v127, v158, v247
	s_lshl_b32 s35, s13, 1
	s_mul_i32 s35, s35, 0xc0
	s_add_u32 s35, s35, 0x80
	s_mul_i32 s34, s56, 0x600
	s_add_u32 s34, s34, s35
	s_add_u32 s38, s0, s34
	s_addc_u32 s39, s1, 0
	s_add_u32 s38, s38, 0xf804100
	s_addc_u32 s39, s39, 0
	v_cvt_pk_bf16_f32 v240, v0, v1
	v_cvt_pk_bf16_f32 v241, v2, v3
	ds_write_b64 v178, v[240:241]
	v_cvt_pk_bf16_f32 v242, v4, v5
	v_cvt_pk_bf16_f32 v243, v6, v7
	ds_write_b64 v179, v[242:243]
	v_cvt_pk_bf16_f32 v244, v8, v9
	v_cvt_pk_bf16_f32 v245, v10, v11
	ds_write_b64 v180, v[244:245]
	v_cvt_pk_bf16_f32 v240, v12, v13
	v_cvt_pk_bf16_f32 v241, v14, v15
	ds_write_b64 v181, v[240:241]
	v_cvt_pk_bf16_f32 v242, v16, v17
	v_cvt_pk_bf16_f32 v243, v18, v19
	ds_write_b64 v188, v[242:243]
	v_cvt_pk_bf16_f32 v244, v20, v21
	v_cvt_pk_bf16_f32 v245, v22, v23
	ds_write_b64 v189, v[244:245]
	v_cvt_pk_bf16_f32 v240, v24, v25
	v_cvt_pk_bf16_f32 v241, v26, v27
	ds_write_b64 v190, v[240:241]
	v_cvt_pk_bf16_f32 v242, v28, v29
	v_cvt_pk_bf16_f32 v243, v30, v31
	ds_write_b64 v191, v[242:243]
	ds_read_b128 v[0:3], v194
	ds_read_b128 v[4:7], v194 offset:1024
	ds_read_b128 v[8:11], v194 offset:2048
	ds_read_b128 v[12:15], v194 offset:3072
	v_cvt_pk_bf16_f32 v244, v32, v33
	v_cvt_pk_bf16_f32 v245, v34, v35
	ds_write_b64 v178, v[244:245]
	v_cvt_pk_bf16_f32 v240, v36, v37
	v_cvt_pk_bf16_f32 v241, v38, v39
	ds_write_b64 v179, v[240:241]
	v_cvt_pk_bf16_f32 v242, v40, v41
	v_cvt_pk_bf16_f32 v243, v42, v43
	ds_write_b64 v180, v[242:243]
	v_cvt_pk_bf16_f32 v244, v44, v45
	v_cvt_pk_bf16_f32 v245, v46, v47
	ds_write_b64 v181, v[244:245]
	v_cvt_pk_bf16_f32 v240, v48, v49
	v_cvt_pk_bf16_f32 v241, v50, v51
	ds_write_b64 v188, v[240:241]
	v_cvt_pk_bf16_f32 v242, v52, v53
	v_cvt_pk_bf16_f32 v243, v54, v55
	ds_write_b64 v189, v[242:243]
	v_cvt_pk_bf16_f32 v244, v56, v57
	v_cvt_pk_bf16_f32 v245, v58, v59
	ds_write_b64 v190, v[244:245]
	v_cvt_pk_bf16_f32 v240, v60, v61
	v_cvt_pk_bf16_f32 v241, v62, v63
	ds_write_b64 v191, v[240:241]
	ds_read_b128 v[32:35], v194
	ds_read_b128 v[36:39], v194 offset:1024
	ds_read_b128 v[40:43], v194 offset:2048
	ds_read_b128 v[44:47], v194 offset:3072
	s_waitcnt lgkmcnt(12)
; DI int crow(int r, int hf) { return (r & 3) + 8 * (r >> 2) + 4 * hf; }
; DI void qkv_phase(const Params& p, int j, char* smem) {
;     ...
;                 const int hq = ((C64 - 512) >> 5) + jn, pos = t & (S_ - 1);
;                 const float xp = __shfl_xor(x, 16);
;                 const float2 cs = rt32[pos * 16 + (l32_ & 15)];
;                 const float o = (l32_ < 16) ? (x * cs.x - xp * cs.y) : (x * cs.x + xp * cs.y);
;                 Qb[(size_t)t * 768 + hq * 96 + 64 + l32_] = f2bf(o);
;     ...
;             if (part == 0) {
; #pragma unroll
;               for (int r = 0; r < 16; ++r) {
;                 const int rr = rl + crow(r, hf_), t = m0_ + rr;
;                 Kb[(size_t)t * LDKB + h * 96 + jn * 32 + l32_] = f2bf(acc[i][jn][r] * rsc[moff + rr]);
;               }
	global_store_dwordx4 v196, v[0:3], s[38:39] nt
	s_add_u32 s38, s38, 0x3000
	s_addc_u32 s39, s39, 0
	global_store_dwordx4 v196, v[4:7], s[38:39] nt
	s_add_u32 s38, s38, 0x3000
	s_addc_u32 s39, s39, 0
	global_store_dwordx4 v196, v[8:11], s[38:39] nt
	s_add_u32 s38, s38, 0x3000
	s_addc_u32 s39, s39, 0
	global_store_dwordx4 v196, v[12:15], s[38:39] nt
	s_add_u32 s38, s38, 0x3000
	s_addc_u32 s39, s39, 0
	v_cvt_pk_bf16_f32 v242, v64, v65
	v_cvt_pk_bf16_f32 v243, v66, v67
	ds_write_b64 v178, v[242:243]
	v_cvt_pk_bf16_f32 v244, v68, v69
	v_cvt_pk_bf16_f32 v245, v70, v71
	ds_write_b64 v179, v[244:245]
	v_cvt_pk_bf16_f32 v240, v72, v73
	v_cvt_pk_bf16_f32 v241, v74, v75
	ds_write_b64 v180, v[240:241]
	v_cvt_pk_bf16_f32 v242, v76, v77
	v_cvt_pk_bf16_f32 v243, v78, v79
	ds_write_b64 v181, v[242:243]
	v_cvt_pk_bf16_f32 v244, v80, v81
	v_cvt_pk_bf16_f32 v245, v82, v83
	ds_write_b64 v188, v[244:245]
	v_cvt_pk_bf16_f32 v240, v84, v85
	v_cvt_pk_bf16_f32 v241, v86, v87
	ds_write_b64 v189, v[240:241]
	v_cvt_pk_bf16_f32 v242, v88, v89
	v_cvt_pk_bf16_f32 v243, v90, v91
	ds_write_b64 v190, v[242:243]
	v_cvt_pk_bf16_f32 v244, v92, v93
	v_cvt_pk_bf16_f32 v245, v94, v95
	ds_write_b64 v191, v[244:245]
	ds_read_b128 v[64:67], v194
	ds_read_b128 v[68:71], v194 offset:1024
	ds_read_b128 v[72:75], v194 offset:2048
	ds_read_b128 v[76:79], v194 offset:3072
	s_waitcnt lgkmcnt(12)
	global_store_dwordx4 v196, v[32:35], s[38:39] nt
	s_add_u32 s38, s38, 0x3000
	s_addc_u32 s39, s39, 0
	global_store_dwordx4 v196, v[36:39], s[38:39] nt
	s_add_u32 s38, s38, 0x3000
	s_addc_u32 s39, s39, 0
	global_store_dwordx4 v196, v[40:43], s[38:39] nt
	s_add_u32 s38, s38, 0x3000
	s_addc_u32 s39, s39, 0
	global_store_dwordx4 v196, v[44:47], s[38:39] nt
	s_add_u32 s38, s38, 0x3000
	s_addc_u32 s39, s39, 0
	v_cvt_pk_bf16_f32 v240, v96, v97
	v_cvt_pk_bf16_f32 v241, v98, v99
	ds_write_b64 v178, v[240:241]
	v_cvt_pk_bf16_f32 v242, v100, v101
	v_cvt_pk_bf16_f32 v243, v102, v103
	ds_write_b64 v179, v[242:243]
	v_cvt_pk_bf16_f32 v244, v104, v105
	v_cvt_pk_bf16_f32 v245, v106, v107
	ds_write_b64 v180, v[244:245]
	v_cvt_pk_bf16_f32 v240, v108, v109
	v_cvt_pk_bf16_f32 v241, v110, v111
	ds_write_b64 v181, v[240:241]
	v_cvt_pk_bf16_f32 v242, v112, v113
	v_cvt_pk_bf16_f32 v243, v114, v115
	ds_write_b64 v188, v[242:243]
	v_cvt_pk_bf16_f32 v244, v116, v117
	v_cvt_pk_bf16_f32 v245, v118, v119
	ds_write_b64 v189, v[244:245]
	v_cvt_pk_bf16_f32 v240, v120, v121
	v_cvt_pk_bf16_f32 v241, v122, v123
	ds_write_b64 v190, v[240:241]
	v_cvt_pk_bf16_f32 v242, v124, v125
	v_cvt_pk_bf16_f32 v243, v126, v127
	ds_write_b64 v191, v[242:243]
	ds_read_b128 v[96:99], v194
	ds_read_b128 v[100:103], v194 offset:1024
	ds_read_b128 v[104:107], v194 offset:2048
	ds_read_b128 v[108:111], v194 offset:3072
	s_waitcnt lgkmcnt(12)
	global_store_dwordx4 v196, v[64:67], s[38:39] nt
	s_add_u32 s38, s38, 0x3000
	s_addc_u32 s39, s39, 0
	global_store_dwordx4 v196, v[68:71], s[38:39] nt
	s_add_u32 s38, s38, 0x3000
	s_addc_u32 s39, s39, 0
	global_store_dwordx4 v196, v[72:75], s[38:39] nt
	s_add_u32 s38, s38, 0x3000
	s_addc_u32 s39, s39, 0
	global_store_dwordx4 v196, v[76:79], s[38:39] nt
	s_add_u32 s38, s38, 0x3000
	s_addc_u32 s39, s39, 0
	s_waitcnt lgkmcnt(0)
	global_store_dwordx4 v196, v[96:99], s[38:39] nt
	s_add_u32 s38, s38, 0x3000
	s_addc_u32 s39, s39, 0
	global_store_dwordx4 v196, v[100:103], s[38:39] nt
	s_add_u32 s38, s38, 0x3000
	s_addc_u32 s39, s39, 0
	global_store_dwordx4 v196, v[104:107], s[38:39] nt
	s_add_u32 s38, s38, 0x3000
	s_addc_u32 s39, s39, 0
	global_store_dwordx4 v196, v[108:111], s[38:39] nt
	s_branch .Lqk_epi_done
.Lqk_epi_kv:
	v_mul_f32_e32 v0, v0, v170
	v_mul_f32_e32 v1, v1, v170
	v_mul_f32_e32 v2, v2, v170
	v_mul_f32_e32 v3, v3, v170
	v_mul_f32_e32 v4, v4, v170
	v_mul_f32_e32 v5, v5, v170
	v_mul_f32_e32 v6, v6, v170
	v_mul_f32_e32 v7, v7, v170
	v_mul_f32_e32 v8, v8, v170
	v_mul_f32_e32 v9, v9, v170
	v_mul_f32_e32 v10, v10, v170
	v_mul_f32_e32 v11, v11, v170
	v_mul_f32_e32 v12, v12, v170
	v_mul_f32_e32 v13, v13, v170
	v_mul_f32_e32 v14, v14, v170
	v_mul_f32_e32 v15, v15, v170
	v_mul_f32_e32 v16, v16, v170
	v_mul_f32_e32 v17, v17, v170
	v_mul_f32_e32 v18, v18, v170
	v_mul_f32_e32 v19, v19, v170
	v_mul_f32_e32 v20, v20, v170
	v_mul_f32_e32 v21, v21, v170
	v_mul_f32_e32 v22, v22, v170
	v_mul_f32_e32 v23, v23, v170
	v_mul_f32_e32 v24, v24, v170
	v_mul_f32_e32 v25, v25, v170
	v_mul_f32_e32 v26, v26, v170
	v_mul_f32_e32 v27, v27, v170
	v_mul_f32_e32 v28, v28, v170
	v_mul_f32_e32 v29, v29, v170
	v_mul_f32_e32 v30, v30, v170
	v_mul_f32_e32 v31, v31, v170
	v_mul_f32_e32 v32, v32, v171
	v_mul_f32_e32 v33, v33, v171
	v_mul_f32_e32 v34, v34, v171
	v_mul_f32_e32 v35, v35, v171
	v_mul_f32_e32 v36, v36, v171
	v_mul_f32_e32 v37, v37, v171
	v_mul_f32_e32 v38, v38, v171
	v_mul_f32_e32 v39, v39, v171
	v_mul_f32_e32 v40, v40, v171
	v_mul_f32_e32 v41, v41, v171
	v_mul_f32_e32 v42, v42, v171
	v_mul_f32_e32 v43, v43, v171
	v_mul_f32_e32 v44, v44, v171
	v_mul_f32_e32 v45, v45, v171
	v_mul_f32_e32 v46, v46, v171
	v_mul_f32_e32 v47, v47, v171
	v_mul_f32_e32 v48, v48, v171
	v_mul_f32_e32 v49, v49, v171
	v_mul_f32_e32 v50, v50, v171
	v_mul_f32_e32 v51, v51, v171
	v_mul_f32_e32 v52, v52, v171
	v_mul_f32_e32 v53, v53, v171
	v_mul_f32_e32 v54, v54, v171
	v_mul_f32_e32 v55, v55, v171
	v_mul_f32_e32 v56, v56, v171
	v_mul_f32_e32 v57, v57, v171
	v_mul_f32_e32 v58, v58, v171
	v_mul_f32_e32 v59, v59, v171
	v_mul_f32_e32 v60, v60, v171
	v_mul_f32_e32 v61, v61, v171
	v_mul_f32_e32 v62, v62, v171
	v_mul_f32_e32 v63, v63, v171
	v_mul_f32_e32 v64, v64, v172
	v_mul_f32_e32 v65, v65, v172
	v_mul_f32_e32 v66, v66, v172
	v_mul_f32_e32 v67, v67, v172
; DI unsigned pack2(float a, float b) { f2_t v = {a, b}; bf2_t r = __builtin_convertvector(v, bf2_t); return __builtin_bit_cast(unsigned, r); }
; DI int crow(int r, int hf) { return (r & 3) + 8 * (r >> 2) + 4 * hf; }
; DI void qkv_phase(const Params& p, int j, char* smem) {
;     ...
;         const int C64 = n0 + wn * 64, h = C64 >> 7, part = (C64 >> 6) & 1;
; #pragma unroll
;         for (int i = 0; i < 2; ++i) {
;           const int rl = wm * 64 + i * 32;
; #pragma unroll
;           for (int jn = 0; jn < 2; ++jn) {
;             if (part == 0) {
; #pragma unroll
;               for (int r = 0; r < 16; ++r) {
;                 const int rr = rl + crow(r, hf_), t = m0_ + rr;
;                 Kb[(size_t)t * LDKB + h * 96 + jn * 32 + l32_] = f2bf(acc[i][jn][r] * rsc[moff + rr]);
;               }
;             } else {
;               const int e = jn * 32 + l32_;
; #pragma unroll
;               for (int qd = 0; qd < 4; ++qd) {
;                 const int rr = rl + 8 * qd + 4 * hf_, t0 = m0_ + rr, b = t0 >> 14, s0 = t0 & (S_ - 1);
;                 uint2 o;
;                 o.x = pack2(acc[i][jn][4 * qd + 0] * rsc[moff + rr + 0], acc[i][jn][4 * qd + 1] * rsc[moff + rr + 1]);
;                 o.y = pack2(acc[i][jn][4 * qd + 2] * rsc[moff + rr + 2], acc[i][jn][4 * qd + 3] * rsc[moff + rr + 3]);
;                 *(uint2*)(Vt + ((size_t)((b * 8 + h) * 64 + e)) * LDV + s0) = o;
;               }
;             }
	v_mul_f32_e32 v68, v68, v172
	v_mul_f32_e32 v69, v69, v172
	v_mul_f32_e32 v70, v70, v172
	v_mul_f32_e32 v71, v71, v172
	v_mul_f32_e32 v72, v72, v172
	v_mul_f32_e32 v73, v73, v172
	v_mul_f32_e32 v74, v74, v172
	v_mul_f32_e32 v75, v75, v172
	v_mul_f32_e32 v76, v76, v172
	v_mul_f32_e32 v77, v77, v172
	v_mul_f32_e32 v78, v78, v172
	v_mul_f32_e32 v79, v79, v172
	v_mul_f32_e32 v80, v80, v172
	v_mul_f32_e32 v81, v81, v172
	v_mul_f32_e32 v82, v82, v172
	v_mul_f32_e32 v83, v83, v172
	v_mul_f32_e32 v84, v84, v172
	v_mul_f32_e32 v85, v85, v172
	v_mul_f32_e32 v86, v86, v172
	v_mul_f32_e32 v87, v87, v172
	v_mul_f32_e32 v88, v88, v172
	v_mul_f32_e32 v89, v89, v172
	v_mul_f32_e32 v90, v90, v172
	v_mul_f32_e32 v91, v91, v172
	v_mul_f32_e32 v92, v92, v172
	v_mul_f32_e32 v93, v93, v172
	v_mul_f32_e32 v94, v94, v172
	v_mul_f32_e32 v95, v95, v172
	v_mul_f32_e32 v96, v96, v173
	v_mul_f32_e32 v97, v97, v173
	v_mul_f32_e32 v98, v98, v173
	v_mul_f32_e32 v99, v99, v173
	v_mul_f32_e32 v100, v100, v173
	v_mul_f32_e32 v101, v101, v173
	v_mul_f32_e32 v102, v102, v173
	v_mul_f32_e32 v103, v103, v173
	v_mul_f32_e32 v104, v104, v173
	v_mul_f32_e32 v105, v105, v173
	v_mul_f32_e32 v106, v106, v173
	v_mul_f32_e32 v107, v107, v173
	v_mul_f32_e32 v108, v108, v173
	v_mul_f32_e32 v109, v109, v173
	v_mul_f32_e32 v110, v110, v173
	v_mul_f32_e32 v111, v111, v173
	v_mul_f32_e32 v112, v112, v173
	v_mul_f32_e32 v113, v113, v173
	v_mul_f32_e32 v114, v114, v173
	v_mul_f32_e32 v115, v115, v173
	v_mul_f32_e32 v116, v116, v173
	v_mul_f32_e32 v117, v117, v173
	v_mul_f32_e32 v118, v118, v173
	v_mul_f32_e32 v119, v119, v173
	v_mul_f32_e32 v120, v120, v173
	v_mul_f32_e32 v121, v121, v173
	v_mul_f32_e32 v122, v122, v173
	v_mul_f32_e32 v123, v123, v173
	v_mul_f32_e32 v124, v124, v173
	v_mul_f32_e32 v125, v125, v173
	v_mul_f32_e32 v126, v126, v173
	v_mul_f32_e32 v127, v127, v173
	s_lshl_b32 s57, s62, 1
	s_lshr_b32 s34, s13, 1
	s_add_u32 s57, s57, s34
	s_bitcmp1_b32 s13, 0
	s_cbranch_scc1 .Lqk_epi_v
	s_mul_i32 s35, s57, 0xc0
	s_mul_i32 s34, s56, 0x680
	s_add_u32 s34, s34, s35
	s_add_u32 s38, s0, s34
	s_addc_u32 s39, s1, 0
	s_add_u32 s38, s38, 0x12804100
	s_addc_u32 s39, s39, 0
	v_cvt_pk_bf16_f32 v240, v0, v1
	v_cvt_pk_bf16_f32 v241, v2, v3
	ds_write_b64 v178, v[240:241]
	v_cvt_pk_bf16_f32 v242, v4, v5
	v_cvt_pk_bf16_f32 v243, v6, v7
	ds_write_b64 v179, v[242:243]
	v_cvt_pk_bf16_f32 v244, v8, v9
	v_cvt_pk_bf16_f32 v245, v10, v11
	ds_write_b64 v180, v[244:245]
	v_cvt_pk_bf16_f32 v240, v12, v13
	v_cvt_pk_bf16_f32 v241, v14, v15
	ds_write_b64 v181, v[240:241]
	v_cvt_pk_bf16_f32 v242, v16, v17
	v_cvt_pk_bf16_f32 v243, v18, v19
	ds_write_b64 v188, v[242:243]
	v_cvt_pk_bf16_f32 v244, v20, v21
	v_cvt_pk_bf16_f32 v245, v22, v23
	ds_write_b64 v189, v[244:245]
	v_cvt_pk_bf16_f32 v240, v24, v25
	v_cvt_pk_bf16_f32 v241, v26, v27
	ds_write_b64 v190, v[240:241]
	v_cvt_pk_bf16_f32 v242, v28, v29
	v_cvt_pk_bf16_f32 v243, v30, v31
	ds_write_b64 v191, v[242:243]
	ds_read_b128 v[0:3], v194
	ds_read_b128 v[4:7], v194 offset:1024
	ds_read_b128 v[8:11], v194 offset:2048
	ds_read_b128 v[12:15], v194 offset:3072
	v_cvt_pk_bf16_f32 v244, v32, v33
	v_cvt_pk_bf16_f32 v245, v34, v35
	ds_write_b64 v178, v[244:245]
	v_cvt_pk_bf16_f32 v240, v36, v37
	v_cvt_pk_bf16_f32 v241, v38, v39
	ds_write_b64 v179, v[240:241]
	v_cvt_pk_bf16_f32 v242, v40, v41
	v_cvt_pk_bf16_f32 v243, v42, v43
	ds_write_b64 v180, v[242:243]
	v_cvt_pk_bf16_f32 v244, v44, v45
	v_cvt_pk_bf16_f32 v245, v46, v47
	ds_write_b64 v181, v[244:245]
	v_cvt_pk_bf16_f32 v240, v48, v49
	v_cvt_pk_bf16_f32 v241, v50, v51
	ds_write_b64 v188, v[240:241]
	v_cvt_pk_bf16_f32 v242, v52, v53
	v_cvt_pk_bf16_f32 v243, v54, v55
	ds_write_b64 v189, v[242:243]
	v_cvt_pk_bf16_f32 v244, v56, v57
	v_cvt_pk_bf16_f32 v245, v58, v59
	ds_write_b64 v190, v[244:245]
	v_cvt_pk_bf16_f32 v240, v60, v61
	v_cvt_pk_bf16_f32 v241, v62, v63
	ds_write_b64 v191, v[240:241]
	ds_read_b128 v[32:35], v194
	ds_read_b128 v[36:39], v194 offset:1024
	ds_read_b128 v[40:43], v194 offset:2048
	ds_read_b128 v[44:47], v194 offset:3072
	s_waitcnt lgkmcnt(12)
	global_store_dwordx4 v197, v[0:3], s[38:39] nt
	s_add_u32 s38, s38, 0x3400
	s_addc_u32 s39, s39, 0
	global_store_dwordx4 v197, v[4:7], s[38:39] nt
	s_add_u32 s38, s38, 0x3400
	s_addc_u32 s39, s39, 0
	global_store_dwordx4 v197, v[8:11], s[38:39] nt
	s_add_u32 s38, s38, 0x3400
	s_addc_u32 s39, s39, 0
	global_store_dwordx4 v197, v[12:15], s[38:39] nt
	s_add_u32 s38, s38, 0x3400
	s_addc_u32 s39, s39, 0
	v_cvt_pk_bf16_f32 v242, v64, v65
	v_cvt_pk_bf16_f32 v243, v66, v67
	ds_write_b64 v178, v[242:243]
	v_cvt_pk_bf16_f32 v244, v68, v69
	v_cvt_pk_bf16_f32 v245, v70, v71
	ds_write_b64 v179, v[244:245]
	v_cvt_pk_bf16_f32 v240, v72, v73
	v_cvt_pk_bf16_f32 v241, v74, v75
	ds_write_b64 v180, v[240:241]
	v_cvt_pk_bf16_f32 v242, v76, v77
	v_cvt_pk_bf16_f32 v243, v78, v79
	ds_write_b64 v181, v[242:243]
	v_cvt_pk_bf16_f32 v244, v80, v81
	v_cvt_pk_bf16_f32 v245, v82, v83
	ds_write_b64 v188, v[244:245]
	v_cvt_pk_bf16_f32 v240, v84, v85
	v_cvt_pk_bf16_f32 v241, v86, v87
	ds_write_b64 v189, v[240:241]
	v_cvt_pk_bf16_f32 v242, v88, v89
	v_cvt_pk_bf16_f32 v243, v90, v91
	ds_write_b64 v190, v[242:243]
	v_cvt_pk_bf16_f32 v244, v92, v93
	v_cvt_pk_bf16_f32 v245, v94, v95
	ds_write_b64 v191, v[244:245]
	ds_read_b128 v[64:67], v194
	ds_read_b128 v[68:71], v194 offset:1024
	ds_read_b128 v[72:75], v194 offset:2048
	ds_read_b128 v[76:79], v194 offset:3072
	s_waitcnt lgkmcnt(12)
; DI unsigned pack2(float a, float b) { f2_t v = {a, b}; bf2_t r = __builtin_convertvector(v, bf2_t); return __builtin_bit_cast(unsigned, r); }
; DI void qkv_phase(const Params& p, int j, char* smem) {
;     ...
;                 Kb[(size_t)t * LDKB + h * 96 + jn * 32 + l32_] = f2bf(acc[i][jn][r] * rsc[moff + rr]);
;               }
;             } else {
;               const int e = jn * 32 + l32_;
; #pragma unroll
;               for (int qd = 0; qd < 4; ++qd) {
;                 const int rr = rl + 8 * qd + 4 * hf_, t0 = m0_ + rr, b = t0 >> 14, s0 = t0 & (S_ - 1);
;                 uint2 o;
;                 o.x = pack2(acc[i][jn][4 * qd + 0] * rsc[moff + rr + 0], acc[i][jn][4 * qd + 1] * rsc[moff + rr + 1]);
;                 o.y = pack2(acc[i][jn][4 * qd + 2] * rsc[moff + rr + 2], acc[i][jn][4 * qd + 3] * rsc[moff + rr + 3]);
;                 *(uint2*)(Vt + ((size_t)((b * 8 + h) * 64 + e)) * LDV + s0) = o;
;               }
;             }
	global_store_dwordx4 v197, v[32:35], s[38:39] nt
	s_add_u32 s38, s38, 0x3400
	s_addc_u32 s39, s39, 0
	global_store_dwordx4 v197, v[36:39], s[38:39] nt
	s_add_u32 s38, s38, 0x3400
	s_addc_u32 s39, s39, 0
	global_store_dwordx4 v197, v[40:43], s[38:39] nt
	s_add_u32 s38, s38, 0x3400
	s_addc_u32 s39, s39, 0
	global_store_dwordx4 v197, v[44:47], s[38:39] nt
	s_add_u32 s38, s38, 0x3400
	s_addc_u32 s39, s39, 0
	v_cvt_pk_bf16_f32 v240, v96, v97
	v_cvt_pk_bf16_f32 v241, v98, v99
	ds_write_b64 v178, v[240:241]
	v_cvt_pk_bf16_f32 v242, v100, v101
	v_cvt_pk_bf16_f32 v243, v102, v103
	ds_write_b64 v179, v[242:243]
	v_cvt_pk_bf16_f32 v244, v104, v105
	v_cvt_pk_bf16_f32 v245, v106, v107
	ds_write_b64 v180, v[244:245]
	v_cvt_pk_bf16_f32 v240, v108, v109
	v_cvt_pk_bf16_f32 v241, v110, v111
	ds_write_b64 v181, v[240:241]
	v_cvt_pk_bf16_f32 v242, v112, v113
	v_cvt_pk_bf16_f32 v243, v114, v115
	ds_write_b64 v188, v[242:243]
	v_cvt_pk_bf16_f32 v244, v116, v117
	v_cvt_pk_bf16_f32 v245, v118, v119
	ds_write_b64 v189, v[244:245]
	v_cvt_pk_bf16_f32 v240, v120, v121
	v_cvt_pk_bf16_f32 v241, v122, v123
	ds_write_b64 v190, v[240:241]
	v_cvt_pk_bf16_f32 v242, v124, v125
	v_cvt_pk_bf16_f32 v243, v126, v127
	ds_write_b64 v191, v[242:243]
	ds_read_b128 v[96:99], v194
	ds_read_b128 v[100:103], v194 offset:1024
	ds_read_b128 v[104:107], v194 offset:2048
	ds_read_b128 v[108:111], v194 offset:3072
	s_waitcnt lgkmcnt(12)
	global_store_dwordx4 v197, v[64:67], s[38:39] nt
	s_add_u32 s38, s38, 0x3400
	s_addc_u32 s39, s39, 0
	global_store_dwordx4 v197, v[68:71], s[38:39] nt
	s_add_u32 s38, s38, 0x3400
	s_addc_u32 s39, s39, 0
	global_store_dwordx4 v197, v[72:75], s[38:39] nt
	s_add_u32 s38, s38, 0x3400
	s_addc_u32 s39, s39, 0
	global_store_dwordx4 v197, v[76:79], s[38:39] nt
	s_add_u32 s38, s38, 0x3400
	s_addc_u32 s39, s39, 0
	s_waitcnt lgkmcnt(0)
	global_store_dwordx4 v197, v[96:99], s[38:39] nt
	s_add_u32 s38, s38, 0x3400
	s_addc_u32 s39, s39, 0
	global_store_dwordx4 v197, v[100:103], s[38:39] nt
	s_add_u32 s38, s38, 0x3400
	s_addc_u32 s39, s39, 0
	global_store_dwordx4 v197, v[104:107], s[38:39] nt
	s_add_u32 s38, s38, 0x3400
	s_addc_u32 s39, s39, 0
	global_store_dwordx4 v197, v[108:111], s[38:39] nt
	s_branch .Lqk_epi_done
.Lqk_epi_v:
	s_lshr_b32 s34, s56, 14
	s_lshl_b32 s34, s34, 3
	s_add_u32 s34, s34, s57
	s_mul_i32 s34, s34, 0x202000
	s_and_b32 s35, s56, 0x3fff
	s_lshl_b32 s35, s35, 1
	s_add_u32 s34, s34, s35
	s_add_u32 s38, s0, s34
	s_addc_u32 s39, s1, 0
	s_add_u32 s38, s38, 0x15c04100
	s_addc_u32 s39, s39, 0
	v_cvt_pk_bf16_f32 v240, v0, v1
	v_cvt_pk_bf16_f32 v241, v2, v3
	ds_write_b16 v235, v240 offset:0
	ds_write_b16_d16_hi v235, v240 offset:64
	ds_write_b16 v235, v241 offset:128
	ds_write_b16_d16_hi v235, v241 offset:192
	v_cvt_pk_bf16_f32 v242, v4, v5
	v_cvt_pk_bf16_f32 v243, v6, v7
	ds_write_b16 v235, v242 offset:512
	ds_write_b16_d16_hi v235, v242 offset:576
	ds_write_b16 v235, v243 offset:640
	ds_write_b16_d16_hi v235, v243 offset:704
	v_cvt_pk_bf16_f32 v244, v8, v9
	v_cvt_pk_bf16_f32 v245, v10, v11
	ds_write_b16 v235, v244 offset:1024
	ds_write_b16_d16_hi v235, v244 offset:1088
	ds_write_b16 v235, v245 offset:1152
	ds_write_b16_d16_hi v235, v245 offset:1216
	v_cvt_pk_bf16_f32 v240, v12, v13
	v_cvt_pk_bf16_f32 v241, v14, v15
	ds_write_b16 v235, v240 offset:1536
	ds_write_b16_d16_hi v235, v240 offset:1600
	ds_write_b16 v235, v241 offset:1664
	ds_write_b16_d16_hi v235, v241 offset:1728
	v_cvt_pk_bf16_f32 v242, v16, v17
	v_cvt_pk_bf16_f32 v243, v18, v19
	ds_write_b16 v235, v242 offset:2048
	ds_write_b16_d16_hi v235, v242 offset:2112
	ds_write_b16 v235, v243 offset:2176
	ds_write_b16_d16_hi v235, v243 offset:2240
	v_cvt_pk_bf16_f32 v244, v20, v21
	v_cvt_pk_bf16_f32 v245, v22, v23
	ds_write_b16 v235, v244 offset:2560
	ds_write_b16_d16_hi v235, v244 offset:2624
	ds_write_b16 v235, v245 offset:2688
	ds_write_b16_d16_hi v235, v245 offset:2752
	v_cvt_pk_bf16_f32 v240, v24, v25
	v_cvt_pk_bf16_f32 v241, v26, v27
	ds_write_b16 v235, v240 offset:3072
	ds_write_b16_d16_hi v235, v240 offset:3136
	ds_write_b16 v235, v241 offset:3200
	ds_write_b16_d16_hi v235, v241 offset:3264
	v_cvt_pk_bf16_f32 v242, v28, v29
	v_cvt_pk_bf16_f32 v243, v30, v31
	ds_write_b16 v235, v242 offset:3584
	ds_write_b16_d16_hi v235, v242 offset:3648
	ds_write_b16 v235, v243 offset:3712
	ds_write_b16_d16_hi v235, v243 offset:3776
	ds_read_b128 v[0:3], v236
	ds_read_b128 v[4:7], v236 offset:1024
	ds_read_b128 v[8:11], v236 offset:2048
	ds_read_b128 v[12:15], v236 offset:3072
	s_waitcnt lgkmcnt(0)
; DI unsigned pack2(float a, float b) { f2_t v = {a, b}; bf2_t r = __builtin_convertvector(v, bf2_t); return __builtin_bit_cast(unsigned, r); }
; DI void qkv_phase(const Params& p, int j, char* smem) {
;     ...
;               const int e = jn * 32 + l32_;
; #pragma unroll
;               for (int qd = 0; qd < 4; ++qd) {
;                 const int rr = rl + 8 * qd + 4 * hf_, t0 = m0_ + rr, b = t0 >> 14, s0 = t0 & (S_ - 1);
;                 uint2 o;
;                 o.x = pack2(acc[i][jn][4 * qd + 0] * rsc[moff + rr + 0], acc[i][jn][4 * qd + 1] * rsc[moff + rr + 1]);
;                 o.y = pack2(acc[i][jn][4 * qd + 2] * rsc[moff + rr + 2], acc[i][jn][4 * qd + 3] * rsc[moff + rr + 3]);
;                 *(uint2*)(Vt + ((size_t)((b * 8 + h) * 64 + e)) * LDV + s0) = o;
;               }
	global_store_dwordx4 v234, v[0:3], s[38:39]
	s_add_u32 s34, s38, 0x80800
	s_addc_u32 s35, s39, 0
	global_store_dwordx4 v234, v[4:7], s[34:35]
	s_add_u32 s34, s38, 0x101000
	s_addc_u32 s35, s39, 0
	global_store_dwordx4 v234, v[8:11], s[34:35]
	s_add_u32 s34, s38, 0x181800
	s_addc_u32 s35, s39, 0
	global_store_dwordx4 v234, v[12:15], s[34:35]
	v_cvt_pk_bf16_f32 v240, v32, v33
	v_cvt_pk_bf16_f32 v241, v34, v35
	ds_write_b16 v235, v240 offset:0
	ds_write_b16_d16_hi v235, v240 offset:64
	ds_write_b16 v235, v241 offset:128
	ds_write_b16_d16_hi v235, v241 offset:192
	v_cvt_pk_bf16_f32 v242, v36, v37
	v_cvt_pk_bf16_f32 v243, v38, v39
	ds_write_b16 v235, v242 offset:512
	ds_write_b16_d16_hi v235, v242 offset:576
	ds_write_b16 v235, v243 offset:640
	ds_write_b16_d16_hi v235, v243 offset:704
	v_cvt_pk_bf16_f32 v244, v40, v41
	v_cvt_pk_bf16_f32 v245, v42, v43
	ds_write_b16 v235, v244 offset:1024
	ds_write_b16_d16_hi v235, v244 offset:1088
	ds_write_b16 v235, v245 offset:1152
	ds_write_b16_d16_hi v235, v245 offset:1216
	v_cvt_pk_bf16_f32 v240, v44, v45
	v_cvt_pk_bf16_f32 v241, v46, v47
	ds_write_b16 v235, v240 offset:1536
	ds_write_b16_d16_hi v235, v240 offset:1600
	ds_write_b16 v235, v241 offset:1664
	ds_write_b16_d16_hi v235, v241 offset:1728
	v_cvt_pk_bf16_f32 v242, v48, v49
	v_cvt_pk_bf16_f32 v243, v50, v51
	ds_write_b16 v235, v242 offset:2048
	ds_write_b16_d16_hi v235, v242 offset:2112
	ds_write_b16 v235, v243 offset:2176
	ds_write_b16_d16_hi v235, v243 offset:2240
	v_cvt_pk_bf16_f32 v244, v52, v53
	v_cvt_pk_bf16_f32 v245, v54, v55
	ds_write_b16 v235, v244 offset:2560
	ds_write_b16_d16_hi v235, v244 offset:2624
	ds_write_b16 v235, v245 offset:2688
	ds_write_b16_d16_hi v235, v245 offset:2752
	v_cvt_pk_bf16_f32 v240, v56, v57
	v_cvt_pk_bf16_f32 v241, v58, v59
	ds_write_b16 v235, v240 offset:3072
	ds_write_b16_d16_hi v235, v240 offset:3136
	ds_write_b16 v235, v241 offset:3200
	ds_write_b16_d16_hi v235, v241 offset:3264
	v_cvt_pk_bf16_f32 v242, v60, v61
	v_cvt_pk_bf16_f32 v243, v62, v63
	ds_write_b16 v235, v242 offset:3584
	ds_write_b16_d16_hi v235, v242 offset:3648
	ds_write_b16 v235, v243 offset:3712
	ds_write_b16_d16_hi v235, v243 offset:3776
	ds_read_b128 v[32:35], v236
	ds_read_b128 v[36:39], v236 offset:1024
	ds_read_b128 v[40:43], v236 offset:2048
	ds_read_b128 v[44:47], v236 offset:3072
	s_waitcnt lgkmcnt(0)
	global_store_dwordx4 v234, v[32:35], s[38:39] offset:64
	s_add_u32 s34, s38, 0x80800
	s_addc_u32 s35, s39, 0
	global_store_dwordx4 v234, v[36:39], s[34:35] offset:64
	s_add_u32 s34, s38, 0x101000
	s_addc_u32 s35, s39, 0
	global_store_dwordx4 v234, v[40:43], s[34:35] offset:64
	s_add_u32 s34, s38, 0x181800
	s_addc_u32 s35, s39, 0
	global_store_dwordx4 v234, v[44:47], s[34:35] offset:64
	v_cvt_pk_bf16_f32 v240, v64, v65
	v_cvt_pk_bf16_f32 v241, v66, v67
	ds_write_b16 v235, v240 offset:0
	ds_write_b16_d16_hi v235, v240 offset:64
	ds_write_b16 v235, v241 offset:128
	ds_write_b16_d16_hi v235, v241 offset:192
	v_cvt_pk_bf16_f32 v242, v68, v69
	v_cvt_pk_bf16_f32 v243, v70, v71
	ds_write_b16 v235, v242 offset:512
	ds_write_b16_d16_hi v235, v242 offset:576
	ds_write_b16 v235, v243 offset:640
	ds_write_b16_d16_hi v235, v243 offset:704
	v_cvt_pk_bf16_f32 v244, v72, v73
	v_cvt_pk_bf16_f32 v245, v74, v75
	ds_write_b16 v235, v244 offset:1024
	ds_write_b16_d16_hi v235, v244 offset:1088
	ds_write_b16 v235, v245 offset:1152
	ds_write_b16_d16_hi v235, v245 offset:1216
	v_cvt_pk_bf16_f32 v240, v76, v77
	v_cvt_pk_bf16_f32 v241, v78, v79
	ds_write_b16 v235, v240 offset:1536
	ds_write_b16_d16_hi v235, v240 offset:1600
	ds_write_b16 v235, v241 offset:1664
	ds_write_b16_d16_hi v235, v241 offset:1728
	v_cvt_pk_bf16_f32 v242, v80, v81
	v_cvt_pk_bf16_f32 v243, v82, v83
	ds_write_b16 v235, v242 offset:2048
	ds_write_b16_d16_hi v235, v242 offset:2112
	ds_write_b16 v235, v243 offset:2176
	ds_write_b16_d16_hi v235, v243 offset:2240
	v_cvt_pk_bf16_f32 v244, v84, v85
	v_cvt_pk_bf16_f32 v245, v86, v87
	ds_write_b16 v235, v244 offset:2560
	ds_write_b16_d16_hi v235, v244 offset:2624
	ds_write_b16 v235, v245 offset:2688
	ds_write_b16_d16_hi v235, v245 offset:2752
	v_cvt_pk_bf16_f32 v240, v88, v89
	v_cvt_pk_bf16_f32 v241, v90, v91
	ds_write_b16 v235, v240 offset:3072
	ds_write_b16_d16_hi v235, v240 offset:3136
	ds_write_b16 v235, v241 offset:3200
	ds_write_b16_d16_hi v235, v241 offset:3264
	v_cvt_pk_bf16_f32 v242, v92, v93
	v_cvt_pk_bf16_f32 v243, v94, v95
	ds_write_b16 v235, v242 offset:3584
	ds_write_b16_d16_hi v235, v242 offset:3648
	ds_write_b16 v235, v243 offset:3712
	ds_write_b16_d16_hi v235, v243 offset:3776
	ds_read_b128 v[64:67], v236
	ds_read_b128 v[68:71], v236 offset:1024
	ds_read_b128 v[72:75], v236 offset:2048
	ds_read_b128 v[76:79], v236 offset:3072
	s_waitcnt lgkmcnt(0)
; DI unsigned pack2(float a, float b) { f2_t v = {a, b}; bf2_t r = __builtin_convertvector(v, bf2_t); return __builtin_bit_cast(unsigned, r); }
; DI void qkv_phase(const Params& p, int j, char* smem) {
;     ...
;   for (int lt0 = blockIdx.x >> 3; lt0 < 16 * 7; lt0 += gridDim.x >> 3) {
;     const bool isq = lt0 < 16 * 3;
;     int mt, nt;
;     if (isq) tile_map(lt0, 16, 3, 16, 1, mt, nt); else tile_map(lt0 - 16 * 3, 16, 4, 8, 4, mt, nt);
;     const int m0 = mt * 256, n0 = nt * 256;
;     ...
;               const int e = jn * 32 + l32_;
; #pragma unroll
;               for (int qd = 0; qd < 4; ++qd) {
;                 const int rr = rl + 8 * qd + 4 * hf_, t0 = m0_ + rr, b = t0 >> 14, s0 = t0 & (S_ - 1);
;                 uint2 o;
;                 o.x = pack2(acc[i][jn][4 * qd + 0] * rsc[moff + rr + 0], acc[i][jn][4 * qd + 1] * rsc[moff + rr + 1]);
;                 o.y = pack2(acc[i][jn][4 * qd + 2] * rsc[moff + rr + 2], acc[i][jn][4 * qd + 3] * rsc[moff + rr + 3]);
;                 *(uint2*)(Vt + ((size_t)((b * 8 + h) * 64 + e)) * LDV + s0) = o;
;               }
	global_store_dwordx4 v234, v[64:67], s[38:39] offset:128
	s_add_u32 s34, s38, 0x80800
	s_addc_u32 s35, s39, 0
	global_store_dwordx4 v234, v[68:71], s[34:35] offset:128
	s_add_u32 s34, s38, 0x101000
	s_addc_u32 s35, s39, 0
	global_store_dwordx4 v234, v[72:75], s[34:35] offset:128
	s_add_u32 s34, s38, 0x181800
	s_addc_u32 s35, s39, 0
	global_store_dwordx4 v234, v[76:79], s[34:35] offset:128
	v_cvt_pk_bf16_f32 v240, v96, v97
	v_cvt_pk_bf16_f32 v241, v98, v99
	ds_write_b16 v235, v240 offset:0
	ds_write_b16_d16_hi v235, v240 offset:64
	ds_write_b16 v235, v241 offset:128
	ds_write_b16_d16_hi v235, v241 offset:192
	v_cvt_pk_bf16_f32 v242, v100, v101
	v_cvt_pk_bf16_f32 v243, v102, v103
	ds_write_b16 v235, v242 offset:512
	ds_write_b16_d16_hi v235, v242 offset:576
	ds_write_b16 v235, v243 offset:640
	ds_write_b16_d16_hi v235, v243 offset:704
	v_cvt_pk_bf16_f32 v244, v104, v105
	v_cvt_pk_bf16_f32 v245, v106, v107
	ds_write_b16 v235, v244 offset:1024
	ds_write_b16_d16_hi v235, v244 offset:1088
	ds_write_b16 v235, v245 offset:1152
	ds_write_b16_d16_hi v235, v245 offset:1216
	v_cvt_pk_bf16_f32 v240, v108, v109
	v_cvt_pk_bf16_f32 v241, v110, v111
	ds_write_b16 v235, v240 offset:1536
	ds_write_b16_d16_hi v235, v240 offset:1600
	ds_write_b16 v235, v241 offset:1664
	ds_write_b16_d16_hi v235, v241 offset:1728
	v_cvt_pk_bf16_f32 v242, v112, v113
	v_cvt_pk_bf16_f32 v243, v114, v115
	ds_write_b16 v235, v242 offset:2048
	ds_write_b16_d16_hi v235, v242 offset:2112
	ds_write_b16 v235, v243 offset:2176
	ds_write_b16_d16_hi v235, v243 offset:2240
	v_cvt_pk_bf16_f32 v244, v116, v117
	v_cvt_pk_bf16_f32 v245, v118, v119
	ds_write_b16 v235, v244 offset:2560
	ds_write_b16_d16_hi v235, v244 offset:2624
	ds_write_b16 v235, v245 offset:2688
	ds_write_b16_d16_hi v235, v245 offset:2752
	v_cvt_pk_bf16_f32 v240, v120, v121
	v_cvt_pk_bf16_f32 v241, v122, v123
	ds_write_b16 v235, v240 offset:3072
	ds_write_b16_d16_hi v235, v240 offset:3136
	ds_write_b16 v235, v241 offset:3200
	ds_write_b16_d16_hi v235, v241 offset:3264
	v_cvt_pk_bf16_f32 v242, v124, v125
	v_cvt_pk_bf16_f32 v243, v126, v127
	ds_write_b16 v235, v242 offset:3584
	ds_write_b16_d16_hi v235, v242 offset:3648
	ds_write_b16 v235, v243 offset:3712
	ds_write_b16_d16_hi v235, v243 offset:3776
	ds_read_b128 v[96:99], v236
	ds_read_b128 v[100:103], v236 offset:1024
	ds_read_b128 v[104:107], v236 offset:2048
	ds_read_b128 v[108:111], v236 offset:3072
	s_waitcnt lgkmcnt(0)
	global_store_dwordx4 v234, v[96:99], s[38:39] offset:192
	s_add_u32 s34, s38, 0x80800
	s_addc_u32 s35, s39, 0
	global_store_dwordx4 v234, v[100:103], s[34:35] offset:192
	s_add_u32 s34, s38, 0x101000
	s_addc_u32 s35, s39, 0
	global_store_dwordx4 v234, v[104:107], s[34:35] offset:192
	s_add_u32 s34, s38, 0x181800
	s_addc_u32 s35, s39, 0
	global_store_dwordx4 v234, v[108:111], s[34:35] offset:192
.Lqk_epi_done:
	s_waitcnt lgkmcnt(0)
	s_add_u32 m0, s14, 0x18000
	s_nop 0
	global_load_lds_dwordx4 v230, s[24:25]
	s_add_u32 m0, s14, 0x18400
	s_nop 0
	global_load_lds_dwordx4 v231, s[24:25]
	s_add_u32 m0, s14, 0x18800
	s_nop 0
	global_load_lds_dwordx4 v232, s[24:25]
	s_add_u32 m0, s14, 0x18c00
	s_nop 0
	global_load_lds_dwordx4 v233, s[24:25]
	s_add_u32 s22, s22, 0x80
	s_addc_u32 s23, s23, 0
	s_add_u32 s24, s24, 0x80
	s_addc_u32 s25, s25, 0
	s_add_u32 s26, s26, 1
	s_cmp_eq_u32 s26, s20
	s_cbranch_scc0 .Lqk8_cadv_done
	s_mov_b32 s26, 0
	s_add_u32 s27, s27, s30
	s_cmp_lt_u32 s27, 0x70
	s_cbranch_scc1 .Lqk8_cadv_new
	s_lshl_b32 s34, s20, 7
	s_sub_u32 s22, s22, s34
	s_subb_u32 s23, s23, 0
	s_sub_u32 s24, s24, s34
	s_subb_u32 s25, s25, 0
	s_branch .Lqk8_cadv_done

; #define RAWBAR() { asm volatile("s_waitcnt vmcnt(0) lgkmcnt(0)" ::: "memory"); __builtin_amdgcn_s_barrier(); }
;     ...
;   if (V != 1) GLDS(0, 0);
;   RAWBAR();
;   for (int kt = 0; kt < nk; kt += 2) {
;     if (V != 1) GLDS(kt + 1, 1);
;     if (V != 2) COMPUTE(0);
;     RAWBAR();
;     if (V != 1) if (kt + 2 < nk) GLDS(kt + 2, 0);
;     if (V != 2) COMPUTE(1);
;     RAWBAR();
;   }
; DI void qkv_phase(const Params& p, int j, char* smem) {
;     ...
;   for (int lt0 = blockIdx.x >> 3; lt0 < 16 * 7; lt0 += gridDim.x >> 3) {
;     const bool isq = lt0 < 16 * 3;
;     int mt, nt;
;     if (isq) tile_map(lt0, 16, 3, 16, 1, mt, nt); else tile_map(lt0 - 16 * 3, 16, 4, 8, 4, mt, nt);
;     const int m0 = mt * 256, n0 = nt * 256;
.Lqk8_cadv_done:
	ds_read_b128 v[128:131], v204
	ds_read_b128 v[132:135], v204 offset:4096
	ds_read_b128 v[136:139], v204 offset:8192
	ds_read_b128 v[140:143], v204 offset:12288
	ds_read_b128 v[162:165], v212
	ds_read_b128 v[166:169], v212 offset:4096
	ds_read_b128 v[144:147], v205
	ds_read_b128 v[148:151], v205 offset:4096
	ds_read_b128 v[152:155], v205 offset:8192
	ds_read_b128 v[156:159], v205 offset:12288
	ds_read_b128 v[170:173], v213
	ds_read_b128 v[174:177], v213 offset:4096
	s_add_u32 s28, s28, s30
	s_cmp_lt_u32 s28, 0x70
	s_cbranch_scc1 .Lqk_tile
	s_waitcnt vmcnt(0) lgkmcnt(0)
	s_barrier
	s_branch .LBB0_599
